# v33 + batched k_s/k_w RMSNorm in P2 + hand-written conv queue item (all loads up front, double-buffered quarters)
# speedup vs baseline: 1.0129x; 1.0027x over previous
.LBB0_415:
	s_and_saveexec_b64 s[10:11], s[0:1]
	s_movk_i32 s14, 0xc00
	s_mov_b32 s15, 0
	v_mad_i64_i32 v[10:11], s[16:17], s20, v65, v[44:45]
	global_load_dwordx4 v[12:15], v[10:11], off
	global_load_dwordx4 v[16:19], v[10:11], off offset:1536
	v_lshl_add_u64 v[10:11], v[10:11], 0, s[14:15]
	global_load_dwordx4 v[20:23], v[10:11], off
	global_load_dwordx4 v[24:27], v[10:11], off offset:1536
	v_lshl_add_u64 v[10:11], v[10:11], 0, s[14:15]
	global_load_dwordx4 v[28:31], v[10:11], off
	global_load_dwordx4 v[32:35], v[10:11], off offset:1536
	v_lshl_add_u64 v[10:11], v[10:11], 0, s[14:15]
	global_load_dwordx4 v[36:39], v[10:11], off
	global_load_dwordx4 v[40:43], v[10:11], off offset:1536
	v_lshl_add_u64 v[10:11], v[10:11], 0, s[14:15]
	global_load_dwordx4 v[68:71], v[10:11], off
	global_load_dwordx4 v[72:75], v[10:11], off offset:1536
	v_lshl_add_u64 v[10:11], v[10:11], 0, s[14:15]
	global_load_dwordx4 v[76:79], v[10:11], off
	global_load_dwordx4 v[80:83], v[10:11], off offset:1536
	v_lshl_add_u64 v[10:11], v[10:11], 0, s[14:15]
	global_load_dwordx4 v[84:87], v[10:11], off
	global_load_dwordx4 v[88:91], v[10:11], off offset:1536
	v_lshl_add_u64 v[10:11], v[10:11], 0, s[14:15]
	global_load_dwordx4 v[92:95], v[10:11], off
	global_load_dwordx4 v[96:99], v[10:11], off offset:1536
	v_mad_i64_i32 v[58:59], s[16:17], s20, v65, v[44:45]
	s_waitcnt vmcnt(12)
	v_lshlrev_b32_e32 v100, 16, v12
	v_and_b32_e32 v101, 0xffff0000, v12
	v_lshlrev_b32_e32 v102, 16, v13
	v_and_b32_e32 v103, 0xffff0000, v13
	v_lshlrev_b32_e32 v104, 16, v14
	v_and_b32_e32 v105, 0xffff0000, v14
	v_lshlrev_b32_e32 v106, 16, v15
	v_and_b32_e32 v107, 0xffff0000, v15
	v_pk_mul_f32 v[10:11], v[100:101], v[100:101]
	v_pk_mul_f32 v[126:127], v[102:103], v[102:103]
	v_add_f32_e32 v8, v10, v11
	v_add_f32_e32 v8, v8, v126
	v_add_f32_e32 v8, v8, v127
	v_pk_mul_f32 v[10:11], v[104:105], v[104:105]
	v_pk_mul_f32 v[126:127], v[106:107], v[106:107]
	v_add_f32_e32 v8, v8, v10
	v_add_f32_e32 v8, v8, v11
	v_add_f32_e32 v8, v8, v126
	v_add_f32_e32 v8, v8, v127
	v_lshlrev_b32_e32 v108, 16, v16
	v_and_b32_e32 v109, 0xffff0000, v16
	v_lshlrev_b32_e32 v110, 16, v17
	v_and_b32_e32 v111, 0xffff0000, v17
	v_lshlrev_b32_e32 v112, 16, v18
	v_and_b32_e32 v113, 0xffff0000, v18
	v_lshlrev_b32_e32 v114, 16, v19
	v_and_b32_e32 v115, 0xffff0000, v19
	v_pk_mul_f32 v[10:11], v[108:109], v[108:109]
	v_pk_mul_f32 v[126:127], v[110:111], v[110:111]
	v_add_f32_e32 v54, v10, v11
	v_add_f32_e32 v54, v54, v126
	v_add_f32_e32 v54, v54, v127
	v_pk_mul_f32 v[10:11], v[112:113], v[112:113]
	v_pk_mul_f32 v[126:127], v[114:115], v[114:115]
	v_add_f32_e32 v54, v54, v10
	v_add_f32_e32 v54, v54, v11
	v_add_f32_e32 v54, v54, v126
	v_add_f32_e32 v54, v54, v127
	v_lshlrev_b32_e32 v46, 16, v20
	v_and_b32_e32 v47, 0xffff0000, v20
	v_lshlrev_b32_e32 v48, 16, v21
	v_and_b32_e32 v49, 0xffff0000, v21
	v_lshlrev_b32_e32 v50, 16, v22
	v_and_b32_e32 v51, 0xffff0000, v22
	v_lshlrev_b32_e32 v52, 16, v23
	v_and_b32_e32 v53, 0xffff0000, v23
	v_pk_mul_f32 v[10:11], v[46:47], v[46:47]
	v_pk_mul_f32 v[126:127], v[48:49], v[48:49]
	v_add_f32_e32 v56, v10, v11
	v_add_f32_e32 v56, v56, v126
	v_add_f32_e32 v56, v56, v127
	v_pk_mul_f32 v[10:11], v[50:51], v[50:51]
	v_pk_mul_f32 v[126:127], v[52:53], v[52:53]
	v_add_f32_e32 v56, v56, v10
	v_add_f32_e32 v56, v56, v11
	v_add_f32_e32 v56, v56, v126
	v_add_f32_e32 v56, v56, v127
	v_lshlrev_b32_e32 v116, 16, v24
	v_and_b32_e32 v117, 0xffff0000, v24
	v_lshlrev_b32_e32 v118, 16, v25
	v_and_b32_e32 v119, 0xffff0000, v25
	v_lshlrev_b32_e32 v120, 16, v26
	v_and_b32_e32 v121, 0xffff0000, v26
	v_lshlrev_b32_e32 v122, 16, v27
	v_and_b32_e32 v123, 0xffff0000, v27
	v_pk_mul_f32 v[10:11], v[116:117], v[116:117]
	v_pk_mul_f32 v[126:127], v[118:119], v[118:119]
	v_add_f32_e32 v124, v10, v11
	v_add_f32_e32 v124, v124, v126
	v_add_f32_e32 v124, v124, v127
	v_pk_mul_f32 v[10:11], v[120:121], v[120:121]
	v_pk_mul_f32 v[126:127], v[122:123], v[122:123]
	v_add_f32_e32 v124, v124, v10
	v_add_f32_e32 v124, v124, v11
	v_add_f32_e32 v124, v124, v126
	v_add_f32_e32 v124, v124, v127
	ds_bpermute_b32 v55, v60, v8
	ds_bpermute_b32 v57, v60, v54
	ds_bpermute_b32 v125, v60, v56
	ds_bpermute_b32 v127, v60, v124
	s_waitcnt lgkmcnt(0)
	v_add_f32_e32 v8, v8, v55
	v_add_f32_e32 v54, v54, v57
	v_add_f32_e32 v56, v56, v125
	v_add_f32_e32 v124, v124, v127
	ds_bpermute_b32 v55, v61, v8
	ds_bpermute_b32 v57, v61, v54
	ds_bpermute_b32 v125, v61, v56
	ds_bpermute_b32 v127, v61, v124
	s_waitcnt lgkmcnt(0)
	v_add_f32_e32 v8, v8, v55
	v_add_f32_e32 v54, v54, v57
	v_add_f32_e32 v56, v56, v125
	v_add_f32_e32 v124, v124, v127
	ds_bpermute_b32 v55, v63, v8
	ds_bpermute_b32 v57, v63, v54
	ds_bpermute_b32 v125, v63, v56
	ds_bpermute_b32 v127, v63, v124
	s_waitcnt lgkmcnt(0)
	v_add_f32_e32 v8, v8, v55
	v_add_f32_e32 v54, v54, v57
	v_add_f32_e32 v56, v56, v125
	v_add_f32_e32 v124, v124, v127
	v_fmamk_f32 v8, v8, 0x3c800000, v64
	v_fmamk_f32 v54, v54, 0x3c800000, v64
	v_fmamk_f32 v56, v56, 0x3c800000, v64
	v_fmamk_f32 v124, v124, 0x3c800000, v64
	v_rsq_f32_e32 v8, v8
	v_rsq_f32_e32 v54, v54
	v_rsq_f32_e32 v56, v56
	v_rsq_f32_e32 v124, v124
	s_nop 0
	v_pk_mul_f32 v[100:101], v[8:9], v[100:101] op_sel_hi:[0,1]
	v_pk_mul_f32 v[102:103], v[8:9], v[102:103] op_sel_hi:[0,1]
	v_pk_mul_f32 v[104:105], v[8:9], v[104:105] op_sel_hi:[0,1]
	v_pk_mul_f32 v[106:107], v[8:9], v[106:107] op_sel_hi:[0,1]
	v_pk_mul_f32 v[100:101], v[4:5], v[100:101]
	v_pk_mul_f32 v[102:103], v[6:7], v[102:103]
	v_pk_mul_f32 v[104:105], v[0:1], v[104:105]
	v_pk_mul_f32 v[106:107], v[2:3], v[106:107]
	v_cvt_pk_bf16_f32 v12, v100, v101
	v_cvt_pk_bf16_f32 v13, v102, v103
	v_cvt_pk_bf16_f32 v14, v104, v105
	v_cvt_pk_bf16_f32 v15, v106, v107
	v_pk_mul_f32 v[108:109], v[54:55], v[108:109] op_sel_hi:[0,1]
	v_pk_mul_f32 v[110:111], v[54:55], v[110:111] op_sel_hi:[0,1]
	v_pk_mul_f32 v[112:113], v[54:55], v[112:113] op_sel_hi:[0,1]
	v_pk_mul_f32 v[114:115], v[54:55], v[114:115] op_sel_hi:[0,1]
	v_pk_mul_f32 v[108:109], v[4:5], v[108:109]
	v_pk_mul_f32 v[110:111], v[6:7], v[110:111]
	v_pk_mul_f32 v[112:113], v[0:1], v[112:113]
	v_pk_mul_f32 v[114:115], v[2:3], v[114:115]
	v_cvt_pk_bf16_f32 v16, v108, v109
	v_cvt_pk_bf16_f32 v17, v110, v111
	v_cvt_pk_bf16_f32 v18, v112, v113
	v_cvt_pk_bf16_f32 v19, v114, v115
	v_pk_mul_f32 v[46:47], v[56:57], v[46:47] op_sel_hi:[0,1]
	v_pk_mul_f32 v[48:49], v[56:57], v[48:49] op_sel_hi:[0,1]
	v_pk_mul_f32 v[50:51], v[56:57], v[50:51] op_sel_hi:[0,1]
	v_pk_mul_f32 v[52:53], v[56:57], v[52:53] op_sel_hi:[0,1]
	v_pk_mul_f32 v[46:47], v[4:5], v[46:47]
	v_pk_mul_f32 v[48:49], v[6:7], v[48:49]
	v_pk_mul_f32 v[50:51], v[0:1], v[50:51]
	v_pk_mul_f32 v[52:53], v[2:3], v[52:53]
	v_cvt_pk_bf16_f32 v20, v46, v47
	v_cvt_pk_bf16_f32 v21, v48, v49
	v_cvt_pk_bf16_f32 v22, v50, v51
	v_cvt_pk_bf16_f32 v23, v52, v53
	v_pk_mul_f32 v[116:117], v[124:125], v[116:117] op_sel_hi:[0,1]
	v_pk_mul_f32 v[118:119], v[124:125], v[118:119] op_sel_hi:[0,1]
	v_pk_mul_f32 v[120:121], v[124:125], v[120:121] op_sel_hi:[0,1]
	v_pk_mul_f32 v[122:123], v[124:125], v[122:123] op_sel_hi:[0,1]
	v_pk_mul_f32 v[116:117], v[4:5], v[116:117]
	v_pk_mul_f32 v[118:119], v[6:7], v[118:119]
	v_pk_mul_f32 v[120:121], v[0:1], v[120:121]
	v_pk_mul_f32 v[122:123], v[2:3], v[122:123]
	v_cvt_pk_bf16_f32 v24, v116, v117
	v_cvt_pk_bf16_f32 v25, v118, v119
	v_cvt_pk_bf16_f32 v26, v120, v121
	v_cvt_pk_bf16_f32 v27, v122, v123
	global_store_dwordx4 v[58:59], v[12:15], off
	global_store_dwordx4 v[58:59], v[16:19], off offset:1536
	global_store_dwordx4 v[58:59], v[20:23], off offset:3072
	v_lshl_add_u64 v[58:59], v[58:59], 0, s[14:15]
	global_store_dwordx4 v[58:59], v[24:27], off offset:1536
	v_lshl_add_u64 v[58:59], v[58:59], 0, s[14:15]
	s_waitcnt vmcnt(12)
	v_lshlrev_b32_e32 v100, 16, v28
	v_and_b32_e32 v101, 0xffff0000, v28
	v_lshlrev_b32_e32 v102, 16, v29
	v_and_b32_e32 v103, 0xffff0000, v29
	v_lshlrev_b32_e32 v104, 16, v30
	v_and_b32_e32 v105, 0xffff0000, v30
	v_lshlrev_b32_e32 v106, 16, v31
	v_and_b32_e32 v107, 0xffff0000, v31
	v_pk_mul_f32 v[10:11], v[100:101], v[100:101]
	v_pk_mul_f32 v[126:127], v[102:103], v[102:103]
	v_add_f32_e32 v8, v10, v11
	v_add_f32_e32 v8, v8, v126
	v_add_f32_e32 v8, v8, v127
	v_pk_mul_f32 v[10:11], v[104:105], v[104:105]
	v_pk_mul_f32 v[126:127], v[106:107], v[106:107]
	v_add_f32_e32 v8, v8, v10
	v_add_f32_e32 v8, v8, v11
	v_add_f32_e32 v8, v8, v126
	v_add_f32_e32 v8, v8, v127
	v_lshlrev_b32_e32 v108, 16, v32
	v_and_b32_e32 v109, 0xffff0000, v32
	v_lshlrev_b32_e32 v110, 16, v33
	v_and_b32_e32 v111, 0xffff0000, v33
	v_lshlrev_b32_e32 v112, 16, v34
	v_and_b32_e32 v113, 0xffff0000, v34
	v_lshlrev_b32_e32 v114, 16, v35
	v_and_b32_e32 v115, 0xffff0000, v35
	v_pk_mul_f32 v[10:11], v[108:109], v[108:109]
	v_pk_mul_f32 v[126:127], v[110:111], v[110:111]
	v_add_f32_e32 v54, v10, v11
	v_add_f32_e32 v54, v54, v126
	v_add_f32_e32 v54, v54, v127
	v_pk_mul_f32 v[10:11], v[112:113], v[112:113]
	v_pk_mul_f32 v[126:127], v[114:115], v[114:115]
	v_add_f32_e32 v54, v54, v10
	v_add_f32_e32 v54, v54, v11
	v_add_f32_e32 v54, v54, v126
	v_add_f32_e32 v54, v54, v127
	v_lshlrev_b32_e32 v46, 16, v36
	v_and_b32_e32 v47, 0xffff0000, v36
	v_lshlrev_b32_e32 v48, 16, v37
	v_and_b32_e32 v49, 0xffff0000, v37
	v_lshlrev_b32_e32 v50, 16, v38
	v_and_b32_e32 v51, 0xffff0000, v38
	v_lshlrev_b32_e32 v52, 16, v39
	v_and_b32_e32 v53, 0xffff0000, v39
	v_pk_mul_f32 v[10:11], v[46:47], v[46:47]
	v_pk_mul_f32 v[126:127], v[48:49], v[48:49]
	v_add_f32_e32 v56, v10, v11
	v_add_f32_e32 v56, v56, v126
	v_add_f32_e32 v56, v56, v127
	v_pk_mul_f32 v[10:11], v[50:51], v[50:51]
	v_pk_mul_f32 v[126:127], v[52:53], v[52:53]
	v_add_f32_e32 v56, v56, v10
	v_add_f32_e32 v56, v56, v11
	v_add_f32_e32 v56, v56, v126
	v_add_f32_e32 v56, v56, v127
	v_lshlrev_b32_e32 v116, 16, v40
	v_and_b32_e32 v117, 0xffff0000, v40
	v_lshlrev_b32_e32 v118, 16, v41
	v_and_b32_e32 v119, 0xffff0000, v41
	v_lshlrev_b32_e32 v120, 16, v42
	v_and_b32_e32 v121, 0xffff0000, v42
	v_lshlrev_b32_e32 v122, 16, v43
	v_and_b32_e32 v123, 0xffff0000, v43
	v_pk_mul_f32 v[10:11], v[116:117], v[116:117]
	v_pk_mul_f32 v[126:127], v[118:119], v[118:119]
	v_add_f32_e32 v124, v10, v11
	v_add_f32_e32 v124, v124, v126
	v_add_f32_e32 v124, v124, v127
	v_pk_mul_f32 v[10:11], v[120:121], v[120:121]
	v_pk_mul_f32 v[126:127], v[122:123], v[122:123]
	v_add_f32_e32 v124, v124, v10
	v_add_f32_e32 v124, v124, v11
	v_add_f32_e32 v124, v124, v126
	v_add_f32_e32 v124, v124, v127
	ds_bpermute_b32 v55, v60, v8
	ds_bpermute_b32 v57, v60, v54
	ds_bpermute_b32 v125, v60, v56
	ds_bpermute_b32 v127, v60, v124
	s_waitcnt lgkmcnt(0)
	v_add_f32_e32 v8, v8, v55
	v_add_f32_e32 v54, v54, v57
	v_add_f32_e32 v56, v56, v125
	v_add_f32_e32 v124, v124, v127
	ds_bpermute_b32 v55, v61, v8
	ds_bpermute_b32 v57, v61, v54
	ds_bpermute_b32 v125, v61, v56
	ds_bpermute_b32 v127, v61, v124
	s_waitcnt lgkmcnt(0)
	v_add_f32_e32 v8, v8, v55
	v_add_f32_e32 v54, v54, v57
	v_add_f32_e32 v56, v56, v125
	v_add_f32_e32 v124, v124, v127
	ds_bpermute_b32 v55, v63, v8
	ds_bpermute_b32 v57, v63, v54
	ds_bpermute_b32 v125, v63, v56
	ds_bpermute_b32 v127, v63, v124
	s_waitcnt lgkmcnt(0)
	v_add_f32_e32 v8, v8, v55
	v_add_f32_e32 v54, v54, v57
	v_add_f32_e32 v56, v56, v125
	v_add_f32_e32 v124, v124, v127
	v_fmamk_f32 v8, v8, 0x3c800000, v64
	v_fmamk_f32 v54, v54, 0x3c800000, v64
	v_fmamk_f32 v56, v56, 0x3c800000, v64
	v_fmamk_f32 v124, v124, 0x3c800000, v64
	v_rsq_f32_e32 v8, v8
	v_rsq_f32_e32 v54, v54
	v_rsq_f32_e32 v56, v56
	v_rsq_f32_e32 v124, v124
	s_nop 0
	v_pk_mul_f32 v[100:101], v[8:9], v[100:101] op_sel_hi:[0,1]
	v_pk_mul_f32 v[102:103], v[8:9], v[102:103] op_sel_hi:[0,1]
	v_pk_mul_f32 v[104:105], v[8:9], v[104:105] op_sel_hi:[0,1]
	v_pk_mul_f32 v[106:107], v[8:9], v[106:107] op_sel_hi:[0,1]
	v_pk_mul_f32 v[100:101], v[4:5], v[100:101]
	v_pk_mul_f32 v[102:103], v[6:7], v[102:103]
	v_pk_mul_f32 v[104:105], v[0:1], v[104:105]
	v_pk_mul_f32 v[106:107], v[2:3], v[106:107]
	v_cvt_pk_bf16_f32 v28, v100, v101
	v_cvt_pk_bf16_f32 v29, v102, v103
	v_cvt_pk_bf16_f32 v30, v104, v105
	v_cvt_pk_bf16_f32 v31, v106, v107
	v_pk_mul_f32 v[108:109], v[54:55], v[108:109] op_sel_hi:[0,1]
	v_pk_mul_f32 v[110:111], v[54:55], v[110:111] op_sel_hi:[0,1]
	v_pk_mul_f32 v[112:113], v[54:55], v[112:113] op_sel_hi:[0,1]
	v_pk_mul_f32 v[114:115], v[54:55], v[114:115] op_sel_hi:[0,1]
	v_pk_mul_f32 v[108:109], v[4:5], v[108:109]
	v_pk_mul_f32 v[110:111], v[6:7], v[110:111]
	v_pk_mul_f32 v[112:113], v[0:1], v[112:113]
	v_pk_mul_f32 v[114:115], v[2:3], v[114:115]
	v_cvt_pk_bf16_f32 v32, v108, v109
	v_cvt_pk_bf16_f32 v33, v110, v111
	v_cvt_pk_bf16_f32 v34, v112, v113
	v_cvt_pk_bf16_f32 v35, v114, v115
	v_pk_mul_f32 v[46:47], v[56:57], v[46:47] op_sel_hi:[0,1]
	v_pk_mul_f32 v[48:49], v[56:57], v[48:49] op_sel_hi:[0,1]
	v_pk_mul_f32 v[50:51], v[56:57], v[50:51] op_sel_hi:[0,1]
	v_pk_mul_f32 v[52:53], v[56:57], v[52:53] op_sel_hi:[0,1]
	v_pk_mul_f32 v[46:47], v[4:5], v[46:47]
	v_pk_mul_f32 v[48:49], v[6:7], v[48:49]
	v_pk_mul_f32 v[50:51], v[0:1], v[50:51]
	v_pk_mul_f32 v[52:53], v[2:3], v[52:53]
	v_cvt_pk_bf16_f32 v36, v46, v47
	v_cvt_pk_bf16_f32 v37, v48, v49
	v_cvt_pk_bf16_f32 v38, v50, v51
	v_cvt_pk_bf16_f32 v39, v52, v53
	v_pk_mul_f32 v[116:117], v[124:125], v[116:117] op_sel_hi:[0,1]
	v_pk_mul_f32 v[118:119], v[124:125], v[118:119] op_sel_hi:[0,1]
	v_pk_mul_f32 v[120:121], v[124:125], v[120:121] op_sel_hi:[0,1]
	v_pk_mul_f32 v[122:123], v[124:125], v[122:123] op_sel_hi:[0,1]
	v_pk_mul_f32 v[116:117], v[4:5], v[116:117]
	v_pk_mul_f32 v[118:119], v[6:7], v[118:119]
	v_pk_mul_f32 v[120:121], v[0:1], v[120:121]
	v_pk_mul_f32 v[122:123], v[2:3], v[122:123]
	v_cvt_pk_bf16_f32 v40, v116, v117
	v_cvt_pk_bf16_f32 v41, v118, v119
	v_cvt_pk_bf16_f32 v42, v120, v121
	v_cvt_pk_bf16_f32 v43, v122, v123
	global_store_dwordx4 v[58:59], v[28:31], off
	global_store_dwordx4 v[58:59], v[32:35], off offset:1536
	global_store_dwordx4 v[58:59], v[36:39], off offset:3072
	v_lshl_add_u64 v[58:59], v[58:59], 0, s[14:15]
	global_store_dwordx4 v[58:59], v[40:43], off offset:1536
	v_lshl_add_u64 v[58:59], v[58:59], 0, s[14:15]
	s_waitcnt vmcnt(12)
	v_lshlrev_b32_e32 v100, 16, v68
	v_and_b32_e32 v101, 0xffff0000, v68
	v_lshlrev_b32_e32 v102, 16, v69
	v_and_b32_e32 v103, 0xffff0000, v69
	v_lshlrev_b32_e32 v104, 16, v70
	v_and_b32_e32 v105, 0xffff0000, v70
	v_lshlrev_b32_e32 v106, 16, v71
	v_and_b32_e32 v107, 0xffff0000, v71
	v_pk_mul_f32 v[10:11], v[100:101], v[100:101]
	v_pk_mul_f32 v[126:127], v[102:103], v[102:103]
	v_add_f32_e32 v8, v10, v11
	v_add_f32_e32 v8, v8, v126
	v_add_f32_e32 v8, v8, v127
	v_pk_mul_f32 v[10:11], v[104:105], v[104:105]
	v_pk_mul_f32 v[126:127], v[106:107], v[106:107]
	v_add_f32_e32 v8, v8, v10
	v_add_f32_e32 v8, v8, v11
	v_add_f32_e32 v8, v8, v126
	v_add_f32_e32 v8, v8, v127
	v_lshlrev_b32_e32 v108, 16, v72
	v_and_b32_e32 v109, 0xffff0000, v72
	v_lshlrev_b32_e32 v110, 16, v73
	v_and_b32_e32 v111, 0xffff0000, v73
	v_lshlrev_b32_e32 v112, 16, v74
	v_and_b32_e32 v113, 0xffff0000, v74
	v_lshlrev_b32_e32 v114, 16, v75
	v_and_b32_e32 v115, 0xffff0000, v75
	v_pk_mul_f32 v[10:11], v[108:109], v[108:109]
	v_pk_mul_f32 v[126:127], v[110:111], v[110:111]
	v_add_f32_e32 v54, v10, v11
	v_add_f32_e32 v54, v54, v126
	v_add_f32_e32 v54, v54, v127
	v_pk_mul_f32 v[10:11], v[112:113], v[112:113]
	v_pk_mul_f32 v[126:127], v[114:115], v[114:115]
	v_add_f32_e32 v54, v54, v10
	v_add_f32_e32 v54, v54, v11
	v_add_f32_e32 v54, v54, v126
	v_add_f32_e32 v54, v54, v127
	v_lshlrev_b32_e32 v46, 16, v76
	v_and_b32_e32 v47, 0xffff0000, v76
	v_lshlrev_b32_e32 v48, 16, v77
	v_and_b32_e32 v49, 0xffff0000, v77
	v_lshlrev_b32_e32 v50, 16, v78
	v_and_b32_e32 v51, 0xffff0000, v78
	v_lshlrev_b32_e32 v52, 16, v79
	v_and_b32_e32 v53, 0xffff0000, v79
	v_pk_mul_f32 v[10:11], v[46:47], v[46:47]
	v_pk_mul_f32 v[126:127], v[48:49], v[48:49]
	v_add_f32_e32 v56, v10, v11
	v_add_f32_e32 v56, v56, v126
	v_add_f32_e32 v56, v56, v127
	v_pk_mul_f32 v[10:11], v[50:51], v[50:51]
	v_pk_mul_f32 v[126:127], v[52:53], v[52:53]
	v_add_f32_e32 v56, v56, v10
	v_add_f32_e32 v56, v56, v11
	v_add_f32_e32 v56, v56, v126
	v_add_f32_e32 v56, v56, v127
	v_lshlrev_b32_e32 v116, 16, v80
	v_and_b32_e32 v117, 0xffff0000, v80
	v_lshlrev_b32_e32 v118, 16, v81
	v_and_b32_e32 v119, 0xffff0000, v81
	v_lshlrev_b32_e32 v120, 16, v82
	v_and_b32_e32 v121, 0xffff0000, v82
	v_lshlrev_b32_e32 v122, 16, v83
	v_and_b32_e32 v123, 0xffff0000, v83
	v_pk_mul_f32 v[10:11], v[116:117], v[116:117]
	v_pk_mul_f32 v[126:127], v[118:119], v[118:119]
	v_add_f32_e32 v124, v10, v11
	v_add_f32_e32 v124, v124, v126
	v_add_f32_e32 v124, v124, v127
	v_pk_mul_f32 v[10:11], v[120:121], v[120:121]
	v_pk_mul_f32 v[126:127], v[122:123], v[122:123]
	v_add_f32_e32 v124, v124, v10
	v_add_f32_e32 v124, v124, v11
	v_add_f32_e32 v124, v124, v126
	v_add_f32_e32 v124, v124, v127
	ds_bpermute_b32 v55, v60, v8
	ds_bpermute_b32 v57, v60, v54
	ds_bpermute_b32 v125, v60, v56
	ds_bpermute_b32 v127, v60, v124
	s_waitcnt lgkmcnt(0)
	v_add_f32_e32 v8, v8, v55
	v_add_f32_e32 v54, v54, v57
	v_add_f32_e32 v56, v56, v125
	v_add_f32_e32 v124, v124, v127
	ds_bpermute_b32 v55, v61, v8
	ds_bpermute_b32 v57, v61, v54
	ds_bpermute_b32 v125, v61, v56
	ds_bpermute_b32 v127, v61, v124
	s_waitcnt lgkmcnt(0)
	v_add_f32_e32 v8, v8, v55
	v_add_f32_e32 v54, v54, v57
	v_add_f32_e32 v56, v56, v125
	v_add_f32_e32 v124, v124, v127
	ds_bpermute_b32 v55, v63, v8
	ds_bpermute_b32 v57, v63, v54
	ds_bpermute_b32 v125, v63, v56
	ds_bpermute_b32 v127, v63, v124
	s_waitcnt lgkmcnt(0)
	v_add_f32_e32 v8, v8, v55
	v_add_f32_e32 v54, v54, v57
	v_add_f32_e32 v56, v56, v125
	v_add_f32_e32 v124, v124, v127
	v_fmamk_f32 v8, v8, 0x3c800000, v64
	v_fmamk_f32 v54, v54, 0x3c800000, v64
	v_fmamk_f32 v56, v56, 0x3c800000, v64
	v_fmamk_f32 v124, v124, 0x3c800000, v64
	v_rsq_f32_e32 v8, v8
	v_rsq_f32_e32 v54, v54
	v_rsq_f32_e32 v56, v56
	v_rsq_f32_e32 v124, v124
	s_nop 0
	v_pk_mul_f32 v[100:101], v[8:9], v[100:101] op_sel_hi:[0,1]
	v_pk_mul_f32 v[102:103], v[8:9], v[102:103] op_sel_hi:[0,1]
	v_pk_mul_f32 v[104:105], v[8:9], v[104:105] op_sel_hi:[0,1]
	v_pk_mul_f32 v[106:107], v[8:9], v[106:107] op_sel_hi:[0,1]
	v_pk_mul_f32 v[100:101], v[4:5], v[100:101]
	v_pk_mul_f32 v[102:103], v[6:7], v[102:103]
	v_pk_mul_f32 v[104:105], v[0:1], v[104:105]
	v_pk_mul_f32 v[106:107], v[2:3], v[106:107]
	v_cvt_pk_bf16_f32 v68, v100, v101
	v_cvt_pk_bf16_f32 v69, v102, v103
	v_cvt_pk_bf16_f32 v70, v104, v105
	v_cvt_pk_bf16_f32 v71, v106, v107
	v_pk_mul_f32 v[108:109], v[54:55], v[108:109] op_sel_hi:[0,1]
	v_pk_mul_f32 v[110:111], v[54:55], v[110:111] op_sel_hi:[0,1]
	v_pk_mul_f32 v[112:113], v[54:55], v[112:113] op_sel_hi:[0,1]
	v_pk_mul_f32 v[114:115], v[54:55], v[114:115] op_sel_hi:[0,1]
	v_pk_mul_f32 v[108:109], v[4:5], v[108:109]
	v_pk_mul_f32 v[110:111], v[6:7], v[110:111]
	v_pk_mul_f32 v[112:113], v[0:1], v[112:113]
	v_pk_mul_f32 v[114:115], v[2:3], v[114:115]
	v_cvt_pk_bf16_f32 v72, v108, v109
	v_cvt_pk_bf16_f32 v73, v110, v111
	v_cvt_pk_bf16_f32 v74, v112, v113
	v_cvt_pk_bf16_f32 v75, v114, v115
	v_pk_mul_f32 v[46:47], v[56:57], v[46:47] op_sel_hi:[0,1]
	v_pk_mul_f32 v[48:49], v[56:57], v[48:49] op_sel_hi:[0,1]
	v_pk_mul_f32 v[50:51], v[56:57], v[50:51] op_sel_hi:[0,1]
	v_pk_mul_f32 v[52:53], v[56:57], v[52:53] op_sel_hi:[0,1]
	v_pk_mul_f32 v[46:47], v[4:5], v[46:47]
	v_pk_mul_f32 v[48:49], v[6:7], v[48:49]
	v_pk_mul_f32 v[50:51], v[0:1], v[50:51]
	v_pk_mul_f32 v[52:53], v[2:3], v[52:53]
	v_cvt_pk_bf16_f32 v76, v46, v47
	v_cvt_pk_bf16_f32 v77, v48, v49
	v_cvt_pk_bf16_f32 v78, v50, v51
	v_cvt_pk_bf16_f32 v79, v52, v53
	v_pk_mul_f32 v[116:117], v[124:125], v[116:117] op_sel_hi:[0,1]
	v_pk_mul_f32 v[118:119], v[124:125], v[118:119] op_sel_hi:[0,1]
	v_pk_mul_f32 v[120:121], v[124:125], v[120:121] op_sel_hi:[0,1]
	v_pk_mul_f32 v[122:123], v[124:125], v[122:123] op_sel_hi:[0,1]
	v_pk_mul_f32 v[116:117], v[4:5], v[116:117]
	v_pk_mul_f32 v[118:119], v[6:7], v[118:119]
	v_pk_mul_f32 v[120:121], v[0:1], v[120:121]
	v_pk_mul_f32 v[122:123], v[2:3], v[122:123]
	v_cvt_pk_bf16_f32 v80, v116, v117
	v_cvt_pk_bf16_f32 v81, v118, v119
	v_cvt_pk_bf16_f32 v82, v120, v121
	v_cvt_pk_bf16_f32 v83, v122, v123
	global_store_dwordx4 v[58:59], v[68:71], off
	global_store_dwordx4 v[58:59], v[72:75], off offset:1536
	global_store_dwordx4 v[58:59], v[76:79], off offset:3072
	v_lshl_add_u64 v[58:59], v[58:59], 0, s[14:15]
	global_store_dwordx4 v[58:59], v[80:83], off offset:1536
	v_lshl_add_u64 v[58:59], v[58:59], 0, s[14:15]
	s_waitcnt vmcnt(12)
	v_lshlrev_b32_e32 v100, 16, v84
	v_and_b32_e32 v101, 0xffff0000, v84
	v_lshlrev_b32_e32 v102, 16, v85
	v_and_b32_e32 v103, 0xffff0000, v85
	v_lshlrev_b32_e32 v104, 16, v86
	v_and_b32_e32 v105, 0xffff0000, v86
	v_lshlrev_b32_e32 v106, 16, v87
	v_and_b32_e32 v107, 0xffff0000, v87
	v_pk_mul_f32 v[10:11], v[100:101], v[100:101]
	v_pk_mul_f32 v[126:127], v[102:103], v[102:103]
	v_add_f32_e32 v8, v10, v11
	v_add_f32_e32 v8, v8, v126
	v_add_f32_e32 v8, v8, v127
	v_pk_mul_f32 v[10:11], v[104:105], v[104:105]
	v_pk_mul_f32 v[126:127], v[106:107], v[106:107]
	v_add_f32_e32 v8, v8, v10
	v_add_f32_e32 v8, v8, v11
	v_add_f32_e32 v8, v8, v126
	v_add_f32_e32 v8, v8, v127
	v_lshlrev_b32_e32 v108, 16, v88
	v_and_b32_e32 v109, 0xffff0000, v88
	v_lshlrev_b32_e32 v110, 16, v89
	v_and_b32_e32 v111, 0xffff0000, v89
	v_lshlrev_b32_e32 v112, 16, v90
	v_and_b32_e32 v113, 0xffff0000, v90
	v_lshlrev_b32_e32 v114, 16, v91
	v_and_b32_e32 v115, 0xffff0000, v91
	v_pk_mul_f32 v[10:11], v[108:109], v[108:109]
	v_pk_mul_f32 v[126:127], v[110:111], v[110:111]
	v_add_f32_e32 v54, v10, v11
	v_add_f32_e32 v54, v54, v126
	v_add_f32_e32 v54, v54, v127
	v_pk_mul_f32 v[10:11], v[112:113], v[112:113]
	v_pk_mul_f32 v[126:127], v[114:115], v[114:115]
	v_add_f32_e32 v54, v54, v10
	v_add_f32_e32 v54, v54, v11
	v_add_f32_e32 v54, v54, v126
	v_add_f32_e32 v54, v54, v127
	v_lshlrev_b32_e32 v46, 16, v92
	v_and_b32_e32 v47, 0xffff0000, v92
	v_lshlrev_b32_e32 v48, 16, v93
	v_and_b32_e32 v49, 0xffff0000, v93
	v_lshlrev_b32_e32 v50, 16, v94
	v_and_b32_e32 v51, 0xffff0000, v94
	v_lshlrev_b32_e32 v52, 16, v95
	v_and_b32_e32 v53, 0xffff0000, v95
	v_pk_mul_f32 v[10:11], v[46:47], v[46:47]
	v_pk_mul_f32 v[126:127], v[48:49], v[48:49]
	v_add_f32_e32 v56, v10, v11
	v_add_f32_e32 v56, v56, v126
	v_add_f32_e32 v56, v56, v127
	v_pk_mul_f32 v[10:11], v[50:51], v[50:51]
	v_pk_mul_f32 v[126:127], v[52:53], v[52:53]
	v_add_f32_e32 v56, v56, v10
	v_add_f32_e32 v56, v56, v11
	v_add_f32_e32 v56, v56, v126
	v_add_f32_e32 v56, v56, v127
	v_lshlrev_b32_e32 v116, 16, v96
	v_and_b32_e32 v117, 0xffff0000, v96
	v_lshlrev_b32_e32 v118, 16, v97
	v_and_b32_e32 v119, 0xffff0000, v97
	v_lshlrev_b32_e32 v120, 16, v98
	v_and_b32_e32 v121, 0xffff0000, v98
	v_lshlrev_b32_e32 v122, 16, v99
	v_and_b32_e32 v123, 0xffff0000, v99
	v_pk_mul_f32 v[10:11], v[116:117], v[116:117]
	v_pk_mul_f32 v[126:127], v[118:119], v[118:119]
	v_add_f32_e32 v124, v10, v11
	v_add_f32_e32 v124, v124, v126
	v_add_f32_e32 v124, v124, v127
	v_pk_mul_f32 v[10:11], v[120:121], v[120:121]
	v_pk_mul_f32 v[126:127], v[122:123], v[122:123]
	v_add_f32_e32 v124, v124, v10
	v_add_f32_e32 v124, v124, v11
	v_add_f32_e32 v124, v124, v126
	v_add_f32_e32 v124, v124, v127
	ds_bpermute_b32 v55, v60, v8
	ds_bpermute_b32 v57, v60, v54
	ds_bpermute_b32 v125, v60, v56
	ds_bpermute_b32 v127, v60, v124
	s_waitcnt lgkmcnt(0)
	v_add_f32_e32 v8, v8, v55
	v_add_f32_e32 v54, v54, v57
	v_add_f32_e32 v56, v56, v125
	v_add_f32_e32 v124, v124, v127
	ds_bpermute_b32 v55, v61, v8
	ds_bpermute_b32 v57, v61, v54
	ds_bpermute_b32 v125, v61, v56
	ds_bpermute_b32 v127, v61, v124
	s_waitcnt lgkmcnt(0)
	v_add_f32_e32 v8, v8, v55
	v_add_f32_e32 v54, v54, v57
	v_add_f32_e32 v56, v56, v125
	v_add_f32_e32 v124, v124, v127
	ds_bpermute_b32 v55, v63, v8
	ds_bpermute_b32 v57, v63, v54
	ds_bpermute_b32 v125, v63, v56
	ds_bpermute_b32 v127, v63, v124
	s_waitcnt lgkmcnt(0)
	v_add_f32_e32 v8, v8, v55
	v_add_f32_e32 v54, v54, v57
	v_add_f32_e32 v56, v56, v125
	v_add_f32_e32 v124, v124, v127
	v_fmamk_f32 v8, v8, 0x3c800000, v64
	v_fmamk_f32 v54, v54, 0x3c800000, v64
	v_fmamk_f32 v56, v56, 0x3c800000, v64
	v_fmamk_f32 v124, v124, 0x3c800000, v64
	v_rsq_f32_e32 v8, v8
	v_rsq_f32_e32 v54, v54
	v_rsq_f32_e32 v56, v56
	v_rsq_f32_e32 v124, v124
	s_nop 0
	v_pk_mul_f32 v[100:101], v[8:9], v[100:101] op_sel_hi:[0,1]
	v_pk_mul_f32 v[102:103], v[8:9], v[102:103] op_sel_hi:[0,1]
	v_pk_mul_f32 v[104:105], v[8:9], v[104:105] op_sel_hi:[0,1]
	v_pk_mul_f32 v[106:107], v[8:9], v[106:107] op_sel_hi:[0,1]
	v_pk_mul_f32 v[100:101], v[4:5], v[100:101]
	v_pk_mul_f32 v[102:103], v[6:7], v[102:103]
	v_pk_mul_f32 v[104:105], v[0:1], v[104:105]
	v_pk_mul_f32 v[106:107], v[2:3], v[106:107]
	v_cvt_pk_bf16_f32 v84, v100, v101
	v_cvt_pk_bf16_f32 v85, v102, v103
	v_cvt_pk_bf16_f32 v86, v104, v105
	v_cvt_pk_bf16_f32 v87, v106, v107
	v_pk_mul_f32 v[108:109], v[54:55], v[108:109] op_sel_hi:[0,1]
	v_pk_mul_f32 v[110:111], v[54:55], v[110:111] op_sel_hi:[0,1]
	v_pk_mul_f32 v[112:113], v[54:55], v[112:113] op_sel_hi:[0,1]
	v_pk_mul_f32 v[114:115], v[54:55], v[114:115] op_sel_hi:[0,1]
	v_pk_mul_f32 v[108:109], v[4:5], v[108:109]
	v_pk_mul_f32 v[110:111], v[6:7], v[110:111]
	v_pk_mul_f32 v[112:113], v[0:1], v[112:113]
	v_pk_mul_f32 v[114:115], v[2:3], v[114:115]
	v_cvt_pk_bf16_f32 v88, v108, v109
	v_cvt_pk_bf16_f32 v89, v110, v111
	v_cvt_pk_bf16_f32 v90, v112, v113
	v_cvt_pk_bf16_f32 v91, v114, v115
	v_pk_mul_f32 v[46:47], v[56:57], v[46:47] op_sel_hi:[0,1]
	v_pk_mul_f32 v[48:49], v[56:57], v[48:49] op_sel_hi:[0,1]
	v_pk_mul_f32 v[50:51], v[56:57], v[50:51] op_sel_hi:[0,1]
	v_pk_mul_f32 v[52:53], v[56:57], v[52:53] op_sel_hi:[0,1]
	v_pk_mul_f32 v[46:47], v[4:5], v[46:47]
	v_pk_mul_f32 v[48:49], v[6:7], v[48:49]
	v_pk_mul_f32 v[50:51], v[0:1], v[50:51]
	v_pk_mul_f32 v[52:53], v[2:3], v[52:53]
	v_cvt_pk_bf16_f32 v92, v46, v47
	v_cvt_pk_bf16_f32 v93, v48, v49
	v_cvt_pk_bf16_f32 v94, v50, v51
	v_cvt_pk_bf16_f32 v95, v52, v53
	v_pk_mul_f32 v[116:117], v[124:125], v[116:117] op_sel_hi:[0,1]
	v_pk_mul_f32 v[118:119], v[124:125], v[118:119] op_sel_hi:[0,1]
	v_pk_mul_f32 v[120:121], v[124:125], v[120:121] op_sel_hi:[0,1]
	v_pk_mul_f32 v[122:123], v[124:125], v[122:123] op_sel_hi:[0,1]
	v_pk_mul_f32 v[116:117], v[4:5], v[116:117]
	v_pk_mul_f32 v[118:119], v[6:7], v[118:119]
	v_pk_mul_f32 v[120:121], v[0:1], v[120:121]
	v_pk_mul_f32 v[122:123], v[2:3], v[122:123]
	v_cvt_pk_bf16_f32 v96, v116, v117
	v_cvt_pk_bf16_f32 v97, v118, v119
	v_cvt_pk_bf16_f32 v98, v120, v121
	v_cvt_pk_bf16_f32 v99, v122, v123
	global_store_dwordx4 v[58:59], v[84:87], off
	global_store_dwordx4 v[58:59], v[88:91], off offset:1536
	global_store_dwordx4 v[58:59], v[92:95], off offset:3072
	v_lshl_add_u64 v[58:59], v[58:59], 0, s[14:15]
	global_store_dwordx4 v[58:59], v[96:99], off offset:1536
	s_or_b64 exec, exec, s[10:11]
	s_branch .LBB0_433

.Lp3_conv:
	v_readfirstlane_b32 s1, v202
	v_mov_b32_e32 v200, v164
	s_lshr_b32 s1, s1, 6
	s_lshl_b32 s52, s0, 3
	s_add_i32 s52, s52, s1
	s_lshl_b32 s20, s52, 4
	v_readlane_b32 s36, v248, 12
	v_readlane_b32 s37, v248, 13
	v_readlane_b32 s8, v249, 3
	v_readlane_b32 s9, v249, 4
	v_and_b32_e32 v2, 63, v202
	v_lshlrev_b32_e32 v3, 5, v2
	v_lshlrev_b32_e32 v2, 4, v2
	s_add_u32 s8, s8, 0x10000000
	s_addc_u32 s9, s9, 0
	s_lshl_b32 s10, s20, 11
	s_mul_i32 s11, s20, 0xc00
	s_add_u32 s12, s74, s10
	s_addc_u32 s13, s75, 0
	s_add_u32 s14, s8, s10
	s_addc_u32 s15, s9, 0
	s_add_u32 s16, s68, s11
	s_addc_u32 s17, s69, 0
	s_add_u32 s16, s16, 0x400
	s_addc_u32 s17, s17, 0
	s_and_b32 s21, s52, 0xff
	s_cmp_lg_u32 s21, 0
	s_cselect_b32 s22, 0xfffff800, 0
	s_cselect_b32 s23, -1, 0
	s_cselect_b32 s24, 0xfffff000, 0
	s_add_u32 s26, s12, s22
	s_addc_u32 s27, s13, s23
	s_add_u32 s28, s12, s24
	s_addc_u32 s29, s13, s23
	s_add_u32 s18, s36, 0x0
	s_addc_u32 s19, s37, 0
	global_load_dwordx4 v[132:135], v3, s[18:19]
	global_load_dwordx4 v[136:139], v3, s[18:19] offset:16
	s_add_u32 s18, s36, 0x1000
	s_addc_u32 s19, s37, 0
	global_load_dwordx4 v[140:143], v3, s[18:19]
	global_load_dwordx4 v[144:147], v3, s[18:19] offset:16
	s_add_u32 s18, s36, 0x2000
	s_addc_u32 s19, s37, 0
	global_load_dwordx4 v[148:151], v3, s[18:19]
	global_load_dwordx4 v[152:155], v3, s[18:19] offset:16
	s_add_u32 s18, s36, 0x800
	s_addc_u32 s19, s37, 0
	global_load_dwordx4 v[156:159], v3, s[18:19]
	global_load_dwordx4 v[160:163], v3, s[18:19] offset:16
	s_add_u32 s18, s36, 0x1800
	s_addc_u32 s19, s37, 0
	global_load_dwordx4 v[164:167], v3, s[18:19]
	global_load_dwordx4 v[168:171], v3, s[18:19] offset:16
	s_add_u32 s18, s36, 0x2800
	s_addc_u32 s19, s37, 0
	global_load_dwordx4 v[172:175], v3, s[18:19]
	global_load_dwordx4 v[176:179], v3, s[18:19] offset:16
	global_load_dwordx4 v[180:183], v2, s[26:27]
	global_load_dwordx4 v[184:187], v2, s[28:29]
	global_load_dwordx4 v[188:191], v2, s[26:27] offset:1024
	global_load_dwordx4 v[196:199], v2, s[28:29] offset:1024
	s_add_u32 s18, s12, 0x0
	s_addc_u32 s19, s13, 0
	s_add_u32 s30, s14, 0x0
	s_addc_u32 s31, s15, 0
	global_load_dwordx4 v[4:7], v2, s[18:19]
	global_load_dwordx4 v[36:39], v2, s[30:31]
	s_add_u32 s18, s12, 0x800
	s_addc_u32 s19, s13, 0
	s_add_u32 s30, s14, 0x800
	s_addc_u32 s31, s15, 0
	global_load_dwordx4 v[8:11], v2, s[18:19]
	global_load_dwordx4 v[40:43], v2, s[30:31]
	s_add_u32 s18, s12, 0x1000
	s_addc_u32 s19, s13, 0
	s_add_u32 s30, s14, 0x1000
	s_addc_u32 s31, s15, 0
	global_load_dwordx4 v[12:15], v2, s[18:19]
	global_load_dwordx4 v[44:47], v2, s[30:31]
	s_add_u32 s18, s12, 0x1800
	s_addc_u32 s19, s13, 0
	s_add_u32 s30, s14, 0x1800
	s_addc_u32 s31, s15, 0
	global_load_dwordx4 v[16:19], v2, s[18:19]
	global_load_dwordx4 v[48:51], v2, s[30:31]
	s_add_u32 s18, s12, 0x2000
	s_addc_u32 s19, s13, 0
	s_add_u32 s30, s14, 0x2000
	s_addc_u32 s31, s15, 0
	global_load_dwordx4 v[20:23], v2, s[18:19]
	global_load_dwordx4 v[52:55], v2, s[30:31]
	s_add_u32 s18, s12, 0x2800
	s_addc_u32 s19, s13, 0
	s_add_u32 s30, s14, 0x2800
	s_addc_u32 s31, s15, 0
	global_load_dwordx4 v[24:27], v2, s[18:19]
	global_load_dwordx4 v[56:59], v2, s[30:31]
	s_add_u32 s18, s12, 0x3000
	s_addc_u32 s19, s13, 0
	s_add_u32 s30, s14, 0x3000
	s_addc_u32 s31, s15, 0
	global_load_dwordx4 v[28:31], v2, s[18:19]
	global_load_dwordx4 v[60:63], v2, s[30:31]
	s_add_u32 s18, s12, 0x3800
	s_addc_u32 s19, s13, 0
	s_add_u32 s30, s14, 0x3800
	s_addc_u32 s31, s15, 0
	global_load_dwordx4 v[32:35], v2, s[18:19]
	global_load_dwordx4 v[64:67], v2, s[30:31]
	s_add_u32 s18, s12, 0x4000
	s_addc_u32 s19, s13, 0
	s_add_u32 s30, s14, 0x4000
	s_addc_u32 s31, s15, 0
	global_load_dwordx4 v[68:71], v2, s[18:19]
	global_load_dwordx4 v[100:103], v2, s[30:31]
	s_add_u32 s18, s12, 0x4800
	s_addc_u32 s19, s13, 0
	s_add_u32 s30, s14, 0x4800
	s_addc_u32 s31, s15, 0
	global_load_dwordx4 v[72:75], v2, s[18:19]
	global_load_dwordx4 v[104:107], v2, s[30:31]
	s_add_u32 s18, s12, 0x5000
	s_addc_u32 s19, s13, 0
	s_add_u32 s30, s14, 0x5000
	s_addc_u32 s31, s15, 0
	global_load_dwordx4 v[76:79], v2, s[18:19]
	global_load_dwordx4 v[108:111], v2, s[30:31]
	s_add_u32 s18, s12, 0x5800
	s_addc_u32 s19, s13, 0
	s_add_u32 s30, s14, 0x5800
	s_addc_u32 s31, s15, 0
	global_load_dwordx4 v[80:83], v2, s[18:19]
	global_load_dwordx4 v[112:115], v2, s[30:31]
	s_add_u32 s18, s12, 0x6000
	s_addc_u32 s19, s13, 0
	s_add_u32 s30, s14, 0x6000
	s_addc_u32 s31, s15, 0
	global_load_dwordx4 v[84:87], v2, s[18:19]
	global_load_dwordx4 v[116:119], v2, s[30:31]
	s_add_u32 s18, s12, 0x6800
	s_addc_u32 s19, s13, 0
	s_add_u32 s30, s14, 0x6800
	s_addc_u32 s31, s15, 0
	global_load_dwordx4 v[88:91], v2, s[18:19]
	global_load_dwordx4 v[120:123], v2, s[30:31]
	s_add_u32 s18, s12, 0x7000
	s_addc_u32 s19, s13, 0
	s_add_u32 s30, s14, 0x7000
	s_addc_u32 s31, s15, 0
	global_load_dwordx4 v[92:95], v2, s[18:19]
	global_load_dwordx4 v[124:127], v2, s[30:31]
	s_add_u32 s18, s12, 0x7800
	s_addc_u32 s19, s13, 0
	s_add_u32 s30, s14, 0x7800
	s_addc_u32 s31, s15, 0
	global_load_dwordx4 v[96:99], v2, s[18:19]
	global_load_dwordx4 v[128:131], v2, s[30:31]
	s_waitcnt vmcnt(16)
	s_cmp_lg_u32 s21, 0
	s_cbranch_scc1 .Lcv_nz0
	v_mov_b32_e32 v180, 0
	v_mov_b32_e32 v181, 0
	v_mov_b32_e32 v182, 0
	v_mov_b32_e32 v183, 0
	v_mov_b32_e32 v184, 0
	v_mov_b32_e32 v185, 0
	v_mov_b32_e32 v186, 0
	v_mov_b32_e32 v187, 0
.Lcv_nz0:
	v_lshlrev_b32_e32 v220, 16, v184
	v_and_b32_e32 v221, 0xffff0000, v184
	v_lshlrev_b32_e32 v222, 16, v185
	v_and_b32_e32 v223, 0xffff0000, v185
	v_lshlrev_b32_e32 v224, 16, v186
	v_and_b32_e32 v225, 0xffff0000, v186
	v_lshlrev_b32_e32 v226, 16, v187
	v_and_b32_e32 v227, 0xffff0000, v187
	v_lshlrev_b32_e32 v228, 16, v180
	v_and_b32_e32 v229, 0xffff0000, v180
	v_lshlrev_b32_e32 v230, 16, v181
	v_and_b32_e32 v231, 0xffff0000, v181
	v_lshlrev_b32_e32 v232, 16, v182
	v_and_b32_e32 v233, 0xffff0000, v182
	v_lshlrev_b32_e32 v234, 16, v183
	v_and_b32_e32 v235, 0xffff0000, v183
	v_lshlrev_b32_e32 v204, 16, v4
	v_and_b32_e32 v205, 0xffff0000, v4
	v_lshlrev_b32_e32 v206, 16, v5
	v_and_b32_e32 v207, 0xffff0000, v5
	v_lshlrev_b32_e32 v208, 16, v6
	v_and_b32_e32 v209, 0xffff0000, v6
	v_lshlrev_b32_e32 v210, 16, v7
	v_and_b32_e32 v211, 0xffff0000, v7
	v_lshlrev_b32_e32 v236, 16, v36
	v_and_b32_e32 v237, 0xffff0000, v36
	v_lshlrev_b32_e32 v238, 16, v37
	v_and_b32_e32 v239, 0xffff0000, v37
	v_lshlrev_b32_e32 v240, 16, v38
	v_and_b32_e32 v241, 0xffff0000, v38
	v_lshlrev_b32_e32 v242, 16, v39
	v_and_b32_e32 v243, 0xffff0000, v39
	v_pk_mul_f32 v[244:245], v[140:141], v[228:229]
	v_pk_fma_f32 v[244:245], v[132:133], v[220:221], v[244:245]
	v_pk_fma_f32 v[244:245], v[148:149], v[204:205], v[244:245]
	v_pk_mul_f32 v[244:245], v[244:245], v[236:237]
	v_cvt_pk_bf16_f32 v212, v244, v245
	v_pk_mul_f32 v[246:247], v[142:143], v[230:231]
	v_pk_fma_f32 v[246:247], v[134:135], v[222:223], v[246:247]
	v_pk_fma_f32 v[246:247], v[150:151], v[206:207], v[246:247]
	v_pk_mul_f32 v[246:247], v[246:247], v[238:239]
	v_cvt_pk_bf16_f32 v213, v246, v247
	v_pk_mul_f32 v[244:245], v[144:145], v[232:233]
	v_pk_fma_f32 v[244:245], v[136:137], v[224:225], v[244:245]
	v_pk_fma_f32 v[244:245], v[152:153], v[208:209], v[244:245]
	v_pk_mul_f32 v[244:245], v[244:245], v[240:241]
	v_cvt_pk_bf16_f32 v214, v244, v245
	v_pk_mul_f32 v[246:247], v[146:147], v[234:235]
	v_pk_fma_f32 v[246:247], v[138:139], v[226:227], v[246:247]
	v_pk_fma_f32 v[246:247], v[154:155], v[210:211], v[246:247]
	v_pk_mul_f32 v[246:247], v[246:247], v[242:243]
	v_cvt_pk_bf16_f32 v215, v246, v247
	s_add_u32 s18, s16, 0x0
	s_addc_u32 s19, s17, 0
	global_store_dwordx4 v2, v[212:215], s[18:19]
	v_lshlrev_b32_e32 v220, 16, v8
	v_and_b32_e32 v221, 0xffff0000, v8
	v_lshlrev_b32_e32 v222, 16, v9
	v_and_b32_e32 v223, 0xffff0000, v9
	v_lshlrev_b32_e32 v224, 16, v10
	v_and_b32_e32 v225, 0xffff0000, v10
	v_lshlrev_b32_e32 v226, 16, v11
	v_and_b32_e32 v227, 0xffff0000, v11
	v_lshlrev_b32_e32 v236, 16, v40
	v_and_b32_e32 v237, 0xffff0000, v40
	v_lshlrev_b32_e32 v238, 16, v41
	v_and_b32_e32 v239, 0xffff0000, v41
	v_lshlrev_b32_e32 v240, 16, v42
	v_and_b32_e32 v241, 0xffff0000, v42
	v_lshlrev_b32_e32 v242, 16, v43
	v_and_b32_e32 v243, 0xffff0000, v43
	v_pk_mul_f32 v[244:245], v[140:141], v[204:205]
	v_pk_fma_f32 v[244:245], v[132:133], v[228:229], v[244:245]
	v_pk_fma_f32 v[244:245], v[148:149], v[220:221], v[244:245]
	v_pk_mul_f32 v[244:245], v[244:245], v[236:237]
	v_cvt_pk_bf16_f32 v216, v244, v245
	v_pk_mul_f32 v[246:247], v[142:143], v[206:207]
	v_pk_fma_f32 v[246:247], v[134:135], v[230:231], v[246:247]
	v_pk_fma_f32 v[246:247], v[150:151], v[222:223], v[246:247]
	v_pk_mul_f32 v[246:247], v[246:247], v[238:239]
	v_cvt_pk_bf16_f32 v217, v246, v247
	v_pk_mul_f32 v[244:245], v[144:145], v[208:209]
	v_pk_fma_f32 v[244:245], v[136:137], v[232:233], v[244:245]
	v_pk_fma_f32 v[244:245], v[152:153], v[224:225], v[244:245]
	v_pk_mul_f32 v[244:245], v[244:245], v[240:241]
	v_cvt_pk_bf16_f32 v218, v244, v245
	v_pk_mul_f32 v[246:247], v[146:147], v[210:211]
	v_pk_fma_f32 v[246:247], v[138:139], v[234:235], v[246:247]
	v_pk_fma_f32 v[246:247], v[154:155], v[226:227], v[246:247]
	v_pk_mul_f32 v[246:247], v[246:247], v[242:243]
	v_cvt_pk_bf16_f32 v219, v246, v247
	s_add_u32 s18, s16, 0xc00
	s_addc_u32 s19, s17, 0
	global_store_dwordx4 v2, v[216:219], s[18:19]
	v_lshlrev_b32_e32 v228, 16, v12
	v_and_b32_e32 v229, 0xffff0000, v12
	v_lshlrev_b32_e32 v230, 16, v13
	v_and_b32_e32 v231, 0xffff0000, v13
	v_lshlrev_b32_e32 v232, 16, v14
	v_and_b32_e32 v233, 0xffff0000, v14
	v_lshlrev_b32_e32 v234, 16, v15
	v_and_b32_e32 v235, 0xffff0000, v15
	v_lshlrev_b32_e32 v236, 16, v44
	v_and_b32_e32 v237, 0xffff0000, v44
	v_lshlrev_b32_e32 v238, 16, v45
	v_and_b32_e32 v239, 0xffff0000, v45
	v_lshlrev_b32_e32 v240, 16, v46
	v_and_b32_e32 v241, 0xffff0000, v46
	v_lshlrev_b32_e32 v242, 16, v47
	v_and_b32_e32 v243, 0xffff0000, v47
	v_pk_mul_f32 v[244:245], v[140:141], v[220:221]
	v_pk_fma_f32 v[244:245], v[132:133], v[204:205], v[244:245]
	v_pk_fma_f32 v[244:245], v[148:149], v[228:229], v[244:245]
	v_pk_mul_f32 v[244:245], v[244:245], v[236:237]
	v_cvt_pk_bf16_f32 v212, v244, v245
	v_pk_mul_f32 v[246:247], v[142:143], v[222:223]
	v_pk_fma_f32 v[246:247], v[134:135], v[206:207], v[246:247]
	v_pk_fma_f32 v[246:247], v[150:151], v[230:231], v[246:247]
	v_pk_mul_f32 v[246:247], v[246:247], v[238:239]
	v_cvt_pk_bf16_f32 v213, v246, v247
	v_pk_mul_f32 v[244:245], v[144:145], v[224:225]
	v_pk_fma_f32 v[244:245], v[136:137], v[208:209], v[244:245]
	v_pk_fma_f32 v[244:245], v[152:153], v[232:233], v[244:245]
	v_pk_mul_f32 v[244:245], v[244:245], v[240:241]
	v_cvt_pk_bf16_f32 v214, v244, v245
	v_pk_mul_f32 v[246:247], v[146:147], v[226:227]
	v_pk_fma_f32 v[246:247], v[138:139], v[210:211], v[246:247]
	v_pk_fma_f32 v[246:247], v[154:155], v[234:235], v[246:247]
	v_pk_mul_f32 v[246:247], v[246:247], v[242:243]
	v_cvt_pk_bf16_f32 v215, v246, v247
	s_add_u32 s18, s16, 0x1800
	s_addc_u32 s19, s17, 0
	global_store_dwordx4 v2, v[212:215], s[18:19]
	v_lshlrev_b32_e32 v204, 16, v16
	v_and_b32_e32 v205, 0xffff0000, v16
	v_lshlrev_b32_e32 v206, 16, v17
	v_and_b32_e32 v207, 0xffff0000, v17
	v_lshlrev_b32_e32 v208, 16, v18
	v_and_b32_e32 v209, 0xffff0000, v18
	v_lshlrev_b32_e32 v210, 16, v19
	v_and_b32_e32 v211, 0xffff0000, v19
	v_lshlrev_b32_e32 v236, 16, v48
	v_and_b32_e32 v237, 0xffff0000, v48
	v_lshlrev_b32_e32 v238, 16, v49
	v_and_b32_e32 v239, 0xffff0000, v49
	v_lshlrev_b32_e32 v240, 16, v50
	v_and_b32_e32 v241, 0xffff0000, v50
	v_lshlrev_b32_e32 v242, 16, v51
	v_and_b32_e32 v243, 0xffff0000, v51
	v_pk_mul_f32 v[244:245], v[140:141], v[228:229]
	v_pk_fma_f32 v[244:245], v[132:133], v[220:221], v[244:245]
	v_pk_fma_f32 v[244:245], v[148:149], v[204:205], v[244:245]
	v_pk_mul_f32 v[244:245], v[244:245], v[236:237]
	v_cvt_pk_bf16_f32 v216, v244, v245
	v_pk_mul_f32 v[246:247], v[142:143], v[230:231]
	v_pk_fma_f32 v[246:247], v[134:135], v[222:223], v[246:247]
	v_pk_fma_f32 v[246:247], v[150:151], v[206:207], v[246:247]
	v_pk_mul_f32 v[246:247], v[246:247], v[238:239]
	v_cvt_pk_bf16_f32 v217, v246, v247
	v_pk_mul_f32 v[244:245], v[144:145], v[232:233]
	v_pk_fma_f32 v[244:245], v[136:137], v[224:225], v[244:245]
	v_pk_fma_f32 v[244:245], v[152:153], v[208:209], v[244:245]
	v_pk_mul_f32 v[244:245], v[244:245], v[240:241]
	v_cvt_pk_bf16_f32 v218, v244, v245
	v_pk_mul_f32 v[246:247], v[146:147], v[234:235]
	v_pk_fma_f32 v[246:247], v[138:139], v[226:227], v[246:247]
	v_pk_fma_f32 v[246:247], v[154:155], v[210:211], v[246:247]
	v_pk_mul_f32 v[246:247], v[246:247], v[242:243]
	v_cvt_pk_bf16_f32 v219, v246, v247
	s_add_u32 s18, s16, 0x2400
	s_addc_u32 s19, s17, 0
	global_store_dwordx4 v2, v[216:219], s[18:19]
	v_lshlrev_b32_e32 v220, 16, v20
	v_and_b32_e32 v221, 0xffff0000, v20
	v_lshlrev_b32_e32 v222, 16, v21
	v_and_b32_e32 v223, 0xffff0000, v21
	v_lshlrev_b32_e32 v224, 16, v22
	v_and_b32_e32 v225, 0xffff0000, v22
	v_lshlrev_b32_e32 v226, 16, v23
	v_and_b32_e32 v227, 0xffff0000, v23
	v_lshlrev_b32_e32 v236, 16, v52
	v_and_b32_e32 v237, 0xffff0000, v52
	v_lshlrev_b32_e32 v238, 16, v53
	v_and_b32_e32 v239, 0xffff0000, v53
	v_lshlrev_b32_e32 v240, 16, v54
	v_and_b32_e32 v241, 0xffff0000, v54
	v_lshlrev_b32_e32 v242, 16, v55
	v_and_b32_e32 v243, 0xffff0000, v55
	v_pk_mul_f32 v[244:245], v[140:141], v[204:205]
	v_pk_fma_f32 v[244:245], v[132:133], v[228:229], v[244:245]
	v_pk_fma_f32 v[244:245], v[148:149], v[220:221], v[244:245]
	v_pk_mul_f32 v[244:245], v[244:245], v[236:237]
	v_cvt_pk_bf16_f32 v212, v244, v245
	v_pk_mul_f32 v[246:247], v[142:143], v[206:207]
	v_pk_fma_f32 v[246:247], v[134:135], v[230:231], v[246:247]
	v_pk_fma_f32 v[246:247], v[150:151], v[222:223], v[246:247]
	v_pk_mul_f32 v[246:247], v[246:247], v[238:239]
	v_cvt_pk_bf16_f32 v213, v246, v247
	v_pk_mul_f32 v[244:245], v[144:145], v[208:209]
	v_pk_fma_f32 v[244:245], v[136:137], v[232:233], v[244:245]
	v_pk_fma_f32 v[244:245], v[152:153], v[224:225], v[244:245]
	v_pk_mul_f32 v[244:245], v[244:245], v[240:241]
	v_cvt_pk_bf16_f32 v214, v244, v245
	v_pk_mul_f32 v[246:247], v[146:147], v[210:211]
	v_pk_fma_f32 v[246:247], v[138:139], v[234:235], v[246:247]
	v_pk_fma_f32 v[246:247], v[154:155], v[226:227], v[246:247]
	v_pk_mul_f32 v[246:247], v[246:247], v[242:243]
	v_cvt_pk_bf16_f32 v215, v246, v247
	s_add_u32 s18, s16, 0x3000
	s_addc_u32 s19, s17, 0
	global_store_dwordx4 v2, v[212:215], s[18:19]
	v_lshlrev_b32_e32 v228, 16, v24
	v_and_b32_e32 v229, 0xffff0000, v24
	v_lshlrev_b32_e32 v230, 16, v25
	v_and_b32_e32 v231, 0xffff0000, v25
	v_lshlrev_b32_e32 v232, 16, v26
	v_and_b32_e32 v233, 0xffff0000, v26
	v_lshlrev_b32_e32 v234, 16, v27
	v_and_b32_e32 v235, 0xffff0000, v27
	v_lshlrev_b32_e32 v236, 16, v56
	v_and_b32_e32 v237, 0xffff0000, v56
	v_lshlrev_b32_e32 v238, 16, v57
	v_and_b32_e32 v239, 0xffff0000, v57
	v_lshlrev_b32_e32 v240, 16, v58
	v_and_b32_e32 v241, 0xffff0000, v58
	v_lshlrev_b32_e32 v242, 16, v59
	v_and_b32_e32 v243, 0xffff0000, v59
	v_pk_mul_f32 v[244:245], v[140:141], v[220:221]
	v_pk_fma_f32 v[244:245], v[132:133], v[204:205], v[244:245]
	v_pk_fma_f32 v[244:245], v[148:149], v[228:229], v[244:245]
	v_pk_mul_f32 v[244:245], v[244:245], v[236:237]
	v_cvt_pk_bf16_f32 v216, v244, v245
	v_pk_mul_f32 v[246:247], v[142:143], v[222:223]
	v_pk_fma_f32 v[246:247], v[134:135], v[206:207], v[246:247]
	v_pk_fma_f32 v[246:247], v[150:151], v[230:231], v[246:247]
	v_pk_mul_f32 v[246:247], v[246:247], v[238:239]
	v_cvt_pk_bf16_f32 v217, v246, v247
	v_pk_mul_f32 v[244:245], v[144:145], v[224:225]
	v_pk_fma_f32 v[244:245], v[136:137], v[208:209], v[244:245]
	v_pk_fma_f32 v[244:245], v[152:153], v[232:233], v[244:245]
	v_pk_mul_f32 v[244:245], v[244:245], v[240:241]
	v_cvt_pk_bf16_f32 v218, v244, v245
	v_pk_mul_f32 v[246:247], v[146:147], v[226:227]
	v_pk_fma_f32 v[246:247], v[138:139], v[210:211], v[246:247]
	v_pk_fma_f32 v[246:247], v[154:155], v[234:235], v[246:247]
	v_pk_mul_f32 v[246:247], v[246:247], v[242:243]
	v_cvt_pk_bf16_f32 v219, v246, v247
	s_add_u32 s18, s16, 0x3c00
	s_addc_u32 s19, s17, 0
	global_store_dwordx4 v2, v[216:219], s[18:19]
	v_lshlrev_b32_e32 v204, 16, v28
	v_and_b32_e32 v205, 0xffff0000, v28
	v_lshlrev_b32_e32 v206, 16, v29
	v_and_b32_e32 v207, 0xffff0000, v29
	v_lshlrev_b32_e32 v208, 16, v30
	v_and_b32_e32 v209, 0xffff0000, v30
	v_lshlrev_b32_e32 v210, 16, v31
	v_and_b32_e32 v211, 0xffff0000, v31
	v_lshlrev_b32_e32 v236, 16, v60
	v_and_b32_e32 v237, 0xffff0000, v60
	v_lshlrev_b32_e32 v238, 16, v61
	v_and_b32_e32 v239, 0xffff0000, v61
	v_lshlrev_b32_e32 v240, 16, v62
	v_and_b32_e32 v241, 0xffff0000, v62
	v_lshlrev_b32_e32 v242, 16, v63
	v_and_b32_e32 v243, 0xffff0000, v63
	v_pk_mul_f32 v[244:245], v[140:141], v[228:229]
	v_pk_fma_f32 v[244:245], v[132:133], v[220:221], v[244:245]
	v_pk_fma_f32 v[244:245], v[148:149], v[204:205], v[244:245]
	v_pk_mul_f32 v[244:245], v[244:245], v[236:237]
	v_cvt_pk_bf16_f32 v212, v244, v245
	v_pk_mul_f32 v[246:247], v[142:143], v[230:231]
	v_pk_fma_f32 v[246:247], v[134:135], v[222:223], v[246:247]
	v_pk_fma_f32 v[246:247], v[150:151], v[206:207], v[246:247]
	v_pk_mul_f32 v[246:247], v[246:247], v[238:239]
	v_cvt_pk_bf16_f32 v213, v246, v247
	v_pk_mul_f32 v[244:245], v[144:145], v[232:233]
	v_pk_fma_f32 v[244:245], v[136:137], v[224:225], v[244:245]
	v_pk_fma_f32 v[244:245], v[152:153], v[208:209], v[244:245]
	v_pk_mul_f32 v[244:245], v[244:245], v[240:241]
	v_cvt_pk_bf16_f32 v214, v244, v245
	v_pk_mul_f32 v[246:247], v[146:147], v[234:235]
	v_pk_fma_f32 v[246:247], v[138:139], v[226:227], v[246:247]
	v_pk_fma_f32 v[246:247], v[154:155], v[210:211], v[246:247]
	v_pk_mul_f32 v[246:247], v[246:247], v[242:243]
	v_cvt_pk_bf16_f32 v215, v246, v247
	s_add_u32 s18, s16, 0x4800
	s_addc_u32 s19, s17, 0
	global_store_dwordx4 v2, v[212:215], s[18:19]
	v_lshlrev_b32_e32 v220, 16, v32
	v_and_b32_e32 v221, 0xffff0000, v32
	v_lshlrev_b32_e32 v222, 16, v33
	v_and_b32_e32 v223, 0xffff0000, v33
	v_lshlrev_b32_e32 v224, 16, v34
	v_and_b32_e32 v225, 0xffff0000, v34
	v_lshlrev_b32_e32 v226, 16, v35
	v_and_b32_e32 v227, 0xffff0000, v35
	v_lshlrev_b32_e32 v236, 16, v64
	v_and_b32_e32 v237, 0xffff0000, v64
	v_lshlrev_b32_e32 v238, 16, v65
	v_and_b32_e32 v239, 0xffff0000, v65
	v_lshlrev_b32_e32 v240, 16, v66
	v_and_b32_e32 v241, 0xffff0000, v66
	v_lshlrev_b32_e32 v242, 16, v67
	v_and_b32_e32 v243, 0xffff0000, v67
	v_pk_mul_f32 v[244:245], v[140:141], v[204:205]
	v_pk_fma_f32 v[244:245], v[132:133], v[228:229], v[244:245]
	v_pk_fma_f32 v[244:245], v[148:149], v[220:221], v[244:245]
	v_pk_mul_f32 v[244:245], v[244:245], v[236:237]
	v_cvt_pk_bf16_f32 v216, v244, v245
	v_pk_mul_f32 v[246:247], v[142:143], v[206:207]
	v_pk_fma_f32 v[246:247], v[134:135], v[230:231], v[246:247]
	v_pk_fma_f32 v[246:247], v[150:151], v[222:223], v[246:247]
	v_pk_mul_f32 v[246:247], v[246:247], v[238:239]
	v_cvt_pk_bf16_f32 v217, v246, v247
	v_pk_mul_f32 v[244:245], v[144:145], v[208:209]
	v_pk_fma_f32 v[244:245], v[136:137], v[232:233], v[244:245]
	v_pk_fma_f32 v[244:245], v[152:153], v[224:225], v[244:245]
	v_pk_mul_f32 v[244:245], v[244:245], v[240:241]
	v_cvt_pk_bf16_f32 v218, v244, v245
	v_pk_mul_f32 v[246:247], v[146:147], v[210:211]
	v_pk_fma_f32 v[246:247], v[138:139], v[234:235], v[246:247]
	v_pk_fma_f32 v[246:247], v[154:155], v[226:227], v[246:247]
	v_pk_mul_f32 v[246:247], v[246:247], v[242:243]
	v_cvt_pk_bf16_f32 v219, v246, v247
	s_add_u32 s18, s16, 0x5400
	s_addc_u32 s19, s17, 0
	global_store_dwordx4 v2, v[216:219], s[18:19]
	s_add_u32 s18, s12, 0x400
	s_addc_u32 s19, s13, 0
	s_add_u32 s30, s14, 0x400
	s_addc_u32 s31, s15, 0
	global_load_dwordx4 v[4:7], v2, s[18:19]
	global_load_dwordx4 v[36:39], v2, s[30:31]
	s_add_u32 s18, s12, 0xc00
	s_addc_u32 s19, s13, 0
	s_add_u32 s30, s14, 0xc00
	s_addc_u32 s31, s15, 0
	global_load_dwordx4 v[8:11], v2, s[18:19]
	global_load_dwordx4 v[40:43], v2, s[30:31]
	s_add_u32 s18, s12, 0x1400
	s_addc_u32 s19, s13, 0
	s_add_u32 s30, s14, 0x1400
	s_addc_u32 s31, s15, 0
	global_load_dwordx4 v[12:15], v2, s[18:19]
	global_load_dwordx4 v[44:47], v2, s[30:31]
	s_add_u32 s18, s12, 0x1c00
	s_addc_u32 s19, s13, 0
	s_add_u32 s30, s14, 0x1c00
	s_addc_u32 s31, s15, 0
	global_load_dwordx4 v[16:19], v2, s[18:19]
	global_load_dwordx4 v[48:51], v2, s[30:31]
	s_add_u32 s18, s12, 0x2400
	s_addc_u32 s19, s13, 0
	s_add_u32 s30, s14, 0x2400
	s_addc_u32 s31, s15, 0
	global_load_dwordx4 v[20:23], v2, s[18:19]
	global_load_dwordx4 v[52:55], v2, s[30:31]
	s_add_u32 s18, s12, 0x2c00
	s_addc_u32 s19, s13, 0
	s_add_u32 s30, s14, 0x2c00
	s_addc_u32 s31, s15, 0
	global_load_dwordx4 v[24:27], v2, s[18:19]
	global_load_dwordx4 v[56:59], v2, s[30:31]
	s_add_u32 s18, s12, 0x3400
	s_addc_u32 s19, s13, 0
	s_add_u32 s30, s14, 0x3400
	s_addc_u32 s31, s15, 0
	global_load_dwordx4 v[28:31], v2, s[18:19]
	global_load_dwordx4 v[60:63], v2, s[30:31]
	s_add_u32 s18, s12, 0x3c00
	s_addc_u32 s19, s13, 0
	s_add_u32 s30, s14, 0x3c00
	s_addc_u32 s31, s15, 0
	global_load_dwordx4 v[32:35], v2, s[18:19]
	global_load_dwordx4 v[64:67], v2, s[30:31]
	s_waitcnt vmcnt(24)
	v_lshlrev_b32_e32 v228, 16, v68
	v_and_b32_e32 v229, 0xffff0000, v68
	v_lshlrev_b32_e32 v230, 16, v69
	v_and_b32_e32 v231, 0xffff0000, v69
	v_lshlrev_b32_e32 v232, 16, v70
	v_and_b32_e32 v233, 0xffff0000, v70
	v_lshlrev_b32_e32 v234, 16, v71
	v_and_b32_e32 v235, 0xffff0000, v71
	v_lshlrev_b32_e32 v236, 16, v100
	v_and_b32_e32 v237, 0xffff0000, v100
	v_lshlrev_b32_e32 v238, 16, v101
	v_and_b32_e32 v239, 0xffff0000, v101
	v_lshlrev_b32_e32 v240, 16, v102
	v_and_b32_e32 v241, 0xffff0000, v102
	v_lshlrev_b32_e32 v242, 16, v103
	v_and_b32_e32 v243, 0xffff0000, v103
	v_pk_mul_f32 v[244:245], v[140:141], v[220:221]
	v_pk_fma_f32 v[244:245], v[132:133], v[204:205], v[244:245]
	v_pk_fma_f32 v[244:245], v[148:149], v[228:229], v[244:245]
	v_pk_mul_f32 v[244:245], v[244:245], v[236:237]
	v_cvt_pk_bf16_f32 v212, v244, v245
	v_pk_mul_f32 v[246:247], v[142:143], v[222:223]
	v_pk_fma_f32 v[246:247], v[134:135], v[206:207], v[246:247]
	v_pk_fma_f32 v[246:247], v[150:151], v[230:231], v[246:247]
	v_pk_mul_f32 v[246:247], v[246:247], v[238:239]
	v_cvt_pk_bf16_f32 v213, v246, v247
	v_pk_mul_f32 v[244:245], v[144:145], v[224:225]
	v_pk_fma_f32 v[244:245], v[136:137], v[208:209], v[244:245]
	v_pk_fma_f32 v[244:245], v[152:153], v[232:233], v[244:245]
	v_pk_mul_f32 v[244:245], v[244:245], v[240:241]
	v_cvt_pk_bf16_f32 v214, v244, v245
	v_pk_mul_f32 v[246:247], v[146:147], v[226:227]
	v_pk_fma_f32 v[246:247], v[138:139], v[210:211], v[246:247]
	v_pk_fma_f32 v[246:247], v[154:155], v[234:235], v[246:247]
	v_pk_mul_f32 v[246:247], v[246:247], v[242:243]
	v_cvt_pk_bf16_f32 v215, v246, v247
	s_add_u32 s18, s16, 0x6000
	s_addc_u32 s19, s17, 0
	global_store_dwordx4 v2, v[212:215], s[18:19]
	v_lshlrev_b32_e32 v204, 16, v72
	v_and_b32_e32 v205, 0xffff0000, v72
	v_lshlrev_b32_e32 v206, 16, v73
	v_and_b32_e32 v207, 0xffff0000, v73
	v_lshlrev_b32_e32 v208, 16, v74
	v_and_b32_e32 v209, 0xffff0000, v74
	v_lshlrev_b32_e32 v210, 16, v75
	v_and_b32_e32 v211, 0xffff0000, v75
	v_lshlrev_b32_e32 v236, 16, v104
	v_and_b32_e32 v237, 0xffff0000, v104
	v_lshlrev_b32_e32 v238, 16, v105
	v_and_b32_e32 v239, 0xffff0000, v105
	v_lshlrev_b32_e32 v240, 16, v106
	v_and_b32_e32 v241, 0xffff0000, v106
	v_lshlrev_b32_e32 v242, 16, v107
	v_and_b32_e32 v243, 0xffff0000, v107
	v_pk_mul_f32 v[244:245], v[140:141], v[228:229]
	v_pk_fma_f32 v[244:245], v[132:133], v[220:221], v[244:245]
	v_pk_fma_f32 v[244:245], v[148:149], v[204:205], v[244:245]
	v_pk_mul_f32 v[244:245], v[244:245], v[236:237]
	v_cvt_pk_bf16_f32 v216, v244, v245
	v_pk_mul_f32 v[246:247], v[142:143], v[230:231]
	v_pk_fma_f32 v[246:247], v[134:135], v[222:223], v[246:247]
	v_pk_fma_f32 v[246:247], v[150:151], v[206:207], v[246:247]
	v_pk_mul_f32 v[246:247], v[246:247], v[238:239]
	v_cvt_pk_bf16_f32 v217, v246, v247
	v_pk_mul_f32 v[244:245], v[144:145], v[232:233]
	v_pk_fma_f32 v[244:245], v[136:137], v[224:225], v[244:245]
	v_pk_fma_f32 v[244:245], v[152:153], v[208:209], v[244:245]
	v_pk_mul_f32 v[244:245], v[244:245], v[240:241]
	v_cvt_pk_bf16_f32 v218, v244, v245
	v_pk_mul_f32 v[246:247], v[146:147], v[234:235]
	v_pk_fma_f32 v[246:247], v[138:139], v[226:227], v[246:247]
	v_pk_fma_f32 v[246:247], v[154:155], v[210:211], v[246:247]
	v_pk_mul_f32 v[246:247], v[246:247], v[242:243]
	v_cvt_pk_bf16_f32 v219, v246, v247
	s_add_u32 s18, s16, 0x6c00
	s_addc_u32 s19, s17, 0
	global_store_dwordx4 v2, v[216:219], s[18:19]
	v_lshlrev_b32_e32 v220, 16, v76
	v_and_b32_e32 v221, 0xffff0000, v76
	v_lshlrev_b32_e32 v222, 16, v77
	v_and_b32_e32 v223, 0xffff0000, v77
	v_lshlrev_b32_e32 v224, 16, v78
	v_and_b32_e32 v225, 0xffff0000, v78
	v_lshlrev_b32_e32 v226, 16, v79
	v_and_b32_e32 v227, 0xffff0000, v79
	v_lshlrev_b32_e32 v236, 16, v108
	v_and_b32_e32 v237, 0xffff0000, v108
	v_lshlrev_b32_e32 v238, 16, v109
	v_and_b32_e32 v239, 0xffff0000, v109
	v_lshlrev_b32_e32 v240, 16, v110
	v_and_b32_e32 v241, 0xffff0000, v110
	v_lshlrev_b32_e32 v242, 16, v111
	v_and_b32_e32 v243, 0xffff0000, v111
	v_pk_mul_f32 v[244:245], v[140:141], v[204:205]
	v_pk_fma_f32 v[244:245], v[132:133], v[228:229], v[244:245]
	v_pk_fma_f32 v[244:245], v[148:149], v[220:221], v[244:245]
	v_pk_mul_f32 v[244:245], v[244:245], v[236:237]
	v_cvt_pk_bf16_f32 v212, v244, v245
	v_pk_mul_f32 v[246:247], v[142:143], v[206:207]
	v_pk_fma_f32 v[246:247], v[134:135], v[230:231], v[246:247]
	v_pk_fma_f32 v[246:247], v[150:151], v[222:223], v[246:247]
	v_pk_mul_f32 v[246:247], v[246:247], v[238:239]
	v_cvt_pk_bf16_f32 v213, v246, v247
	v_pk_mul_f32 v[244:245], v[144:145], v[208:209]
	v_pk_fma_f32 v[244:245], v[136:137], v[232:233], v[244:245]
	v_pk_fma_f32 v[244:245], v[152:153], v[224:225], v[244:245]
	v_pk_mul_f32 v[244:245], v[244:245], v[240:241]
	v_cvt_pk_bf16_f32 v214, v244, v245
	v_pk_mul_f32 v[246:247], v[146:147], v[210:211]
	v_pk_fma_f32 v[246:247], v[138:139], v[234:235], v[246:247]
	v_pk_fma_f32 v[246:247], v[154:155], v[226:227], v[246:247]
	v_pk_mul_f32 v[246:247], v[246:247], v[242:243]
	v_cvt_pk_bf16_f32 v215, v246, v247
	s_add_u32 s18, s16, 0x7800
	s_addc_u32 s19, s17, 0
	global_store_dwordx4 v2, v[212:215], s[18:19]
	v_lshlrev_b32_e32 v228, 16, v80
	v_and_b32_e32 v229, 0xffff0000, v80
	v_lshlrev_b32_e32 v230, 16, v81
	v_and_b32_e32 v231, 0xffff0000, v81
	v_lshlrev_b32_e32 v232, 16, v82
	v_and_b32_e32 v233, 0xffff0000, v82
	v_lshlrev_b32_e32 v234, 16, v83
	v_and_b32_e32 v235, 0xffff0000, v83
	v_lshlrev_b32_e32 v236, 16, v112
	v_and_b32_e32 v237, 0xffff0000, v112
	v_lshlrev_b32_e32 v238, 16, v113
	v_and_b32_e32 v239, 0xffff0000, v113
	v_lshlrev_b32_e32 v240, 16, v114
	v_and_b32_e32 v241, 0xffff0000, v114
	v_lshlrev_b32_e32 v242, 16, v115
	v_and_b32_e32 v243, 0xffff0000, v115
	v_pk_mul_f32 v[244:245], v[140:141], v[220:221]
	v_pk_fma_f32 v[244:245], v[132:133], v[204:205], v[244:245]
	v_pk_fma_f32 v[244:245], v[148:149], v[228:229], v[244:245]
	v_pk_mul_f32 v[244:245], v[244:245], v[236:237]
	v_cvt_pk_bf16_f32 v216, v244, v245
	v_pk_mul_f32 v[246:247], v[142:143], v[222:223]
	v_pk_fma_f32 v[246:247], v[134:135], v[206:207], v[246:247]
	v_pk_fma_f32 v[246:247], v[150:151], v[230:231], v[246:247]
	v_pk_mul_f32 v[246:247], v[246:247], v[238:239]
	v_cvt_pk_bf16_f32 v217, v246, v247
	v_pk_mul_f32 v[244:245], v[144:145], v[224:225]
	v_pk_fma_f32 v[244:245], v[136:137], v[208:209], v[244:245]
	v_pk_fma_f32 v[244:245], v[152:153], v[232:233], v[244:245]
	v_pk_mul_f32 v[244:245], v[244:245], v[240:241]
	v_cvt_pk_bf16_f32 v218, v244, v245
	v_pk_mul_f32 v[246:247], v[146:147], v[226:227]
	v_pk_fma_f32 v[246:247], v[138:139], v[210:211], v[246:247]
	v_pk_fma_f32 v[246:247], v[154:155], v[234:235], v[246:247]
	v_pk_mul_f32 v[246:247], v[246:247], v[242:243]
	v_cvt_pk_bf16_f32 v219, v246, v247
	s_add_u32 s18, s16, 0x8400
	s_addc_u32 s19, s17, 0
	global_store_dwordx4 v2, v[216:219], s[18:19]
	v_lshlrev_b32_e32 v204, 16, v84
	v_and_b32_e32 v205, 0xffff0000, v84
	v_lshlrev_b32_e32 v206, 16, v85
	v_and_b32_e32 v207, 0xffff0000, v85
	v_lshlrev_b32_e32 v208, 16, v86
	v_and_b32_e32 v209, 0xffff0000, v86
	v_lshlrev_b32_e32 v210, 16, v87
	v_and_b32_e32 v211, 0xffff0000, v87
	v_lshlrev_b32_e32 v236, 16, v116
	v_and_b32_e32 v237, 0xffff0000, v116
	v_lshlrev_b32_e32 v238, 16, v117
	v_and_b32_e32 v239, 0xffff0000, v117
	v_lshlrev_b32_e32 v240, 16, v118
	v_and_b32_e32 v241, 0xffff0000, v118
	v_lshlrev_b32_e32 v242, 16, v119
	v_and_b32_e32 v243, 0xffff0000, v119
	v_pk_mul_f32 v[244:245], v[140:141], v[228:229]
	v_pk_fma_f32 v[244:245], v[132:133], v[220:221], v[244:245]
	v_pk_fma_f32 v[244:245], v[148:149], v[204:205], v[244:245]
	v_pk_mul_f32 v[244:245], v[244:245], v[236:237]
	v_cvt_pk_bf16_f32 v212, v244, v245
	v_pk_mul_f32 v[246:247], v[142:143], v[230:231]
	v_pk_fma_f32 v[246:247], v[134:135], v[222:223], v[246:247]
	v_pk_fma_f32 v[246:247], v[150:151], v[206:207], v[246:247]
	v_pk_mul_f32 v[246:247], v[246:247], v[238:239]
	v_cvt_pk_bf16_f32 v213, v246, v247
	v_pk_mul_f32 v[244:245], v[144:145], v[232:233]
	v_pk_fma_f32 v[244:245], v[136:137], v[224:225], v[244:245]
	v_pk_fma_f32 v[244:245], v[152:153], v[208:209], v[244:245]
	v_pk_mul_f32 v[244:245], v[244:245], v[240:241]
	v_cvt_pk_bf16_f32 v214, v244, v245
	v_pk_mul_f32 v[246:247], v[146:147], v[234:235]
	v_pk_fma_f32 v[246:247], v[138:139], v[226:227], v[246:247]
	v_pk_fma_f32 v[246:247], v[154:155], v[210:211], v[246:247]
	v_pk_mul_f32 v[246:247], v[246:247], v[242:243]
	v_cvt_pk_bf16_f32 v215, v246, v247
	s_add_u32 s18, s16, 0x9000
	s_addc_u32 s19, s17, 0
	global_store_dwordx4 v2, v[212:215], s[18:19]
	v_lshlrev_b32_e32 v220, 16, v88
	v_and_b32_e32 v221, 0xffff0000, v88
	v_lshlrev_b32_e32 v222, 16, v89
	v_and_b32_e32 v223, 0xffff0000, v89
	v_lshlrev_b32_e32 v224, 16, v90
	v_and_b32_e32 v225, 0xffff0000, v90
	v_lshlrev_b32_e32 v226, 16, v91
	v_and_b32_e32 v227, 0xffff0000, v91
	v_lshlrev_b32_e32 v236, 16, v120
	v_and_b32_e32 v237, 0xffff0000, v120
	v_lshlrev_b32_e32 v238, 16, v121
	v_and_b32_e32 v239, 0xffff0000, v121
	v_lshlrev_b32_e32 v240, 16, v122
	v_and_b32_e32 v241, 0xffff0000, v122
	v_lshlrev_b32_e32 v242, 16, v123
	v_and_b32_e32 v243, 0xffff0000, v123
	v_pk_mul_f32 v[244:245], v[140:141], v[204:205]
	v_pk_fma_f32 v[244:245], v[132:133], v[228:229], v[244:245]
	v_pk_fma_f32 v[244:245], v[148:149], v[220:221], v[244:245]
	v_pk_mul_f32 v[244:245], v[244:245], v[236:237]
	v_cvt_pk_bf16_f32 v216, v244, v245
	v_pk_mul_f32 v[246:247], v[142:143], v[206:207]
	v_pk_fma_f32 v[246:247], v[134:135], v[230:231], v[246:247]
	v_pk_fma_f32 v[246:247], v[150:151], v[222:223], v[246:247]
	v_pk_mul_f32 v[246:247], v[246:247], v[238:239]
	v_cvt_pk_bf16_f32 v217, v246, v247
	v_pk_mul_f32 v[244:245], v[144:145], v[208:209]
	v_pk_fma_f32 v[244:245], v[136:137], v[232:233], v[244:245]
	v_pk_fma_f32 v[244:245], v[152:153], v[224:225], v[244:245]
	v_pk_mul_f32 v[244:245], v[244:245], v[240:241]
	v_cvt_pk_bf16_f32 v218, v244, v245
	v_pk_mul_f32 v[246:247], v[146:147], v[210:211]
	v_pk_fma_f32 v[246:247], v[138:139], v[234:235], v[246:247]
	v_pk_fma_f32 v[246:247], v[154:155], v[226:227], v[246:247]
	v_pk_mul_f32 v[246:247], v[246:247], v[242:243]
	v_cvt_pk_bf16_f32 v219, v246, v247
	s_add_u32 s18, s16, 0x9c00
	s_addc_u32 s19, s17, 0
	global_store_dwordx4 v2, v[216:219], s[18:19]
	v_lshlrev_b32_e32 v228, 16, v92
	v_and_b32_e32 v229, 0xffff0000, v92
	v_lshlrev_b32_e32 v230, 16, v93
	v_and_b32_e32 v231, 0xffff0000, v93
	v_lshlrev_b32_e32 v232, 16, v94
	v_and_b32_e32 v233, 0xffff0000, v94
	v_lshlrev_b32_e32 v234, 16, v95
	v_and_b32_e32 v235, 0xffff0000, v95
	v_lshlrev_b32_e32 v236, 16, v124
	v_and_b32_e32 v237, 0xffff0000, v124
	v_lshlrev_b32_e32 v238, 16, v125
	v_and_b32_e32 v239, 0xffff0000, v125
	v_lshlrev_b32_e32 v240, 16, v126
	v_and_b32_e32 v241, 0xffff0000, v126
	v_lshlrev_b32_e32 v242, 16, v127
	v_and_b32_e32 v243, 0xffff0000, v127
	v_pk_mul_f32 v[244:245], v[140:141], v[220:221]
	v_pk_fma_f32 v[244:245], v[132:133], v[204:205], v[244:245]
	v_pk_fma_f32 v[244:245], v[148:149], v[228:229], v[244:245]
	v_pk_mul_f32 v[244:245], v[244:245], v[236:237]
	v_cvt_pk_bf16_f32 v212, v244, v245
	v_pk_mul_f32 v[246:247], v[142:143], v[222:223]
	v_pk_fma_f32 v[246:247], v[134:135], v[206:207], v[246:247]
	v_pk_fma_f32 v[246:247], v[150:151], v[230:231], v[246:247]
	v_pk_mul_f32 v[246:247], v[246:247], v[238:239]
	v_cvt_pk_bf16_f32 v213, v246, v247
	v_pk_mul_f32 v[244:245], v[144:145], v[224:225]
	v_pk_fma_f32 v[244:245], v[136:137], v[208:209], v[244:245]
	v_pk_fma_f32 v[244:245], v[152:153], v[232:233], v[244:245]
	v_pk_mul_f32 v[244:245], v[244:245], v[240:241]
	v_cvt_pk_bf16_f32 v214, v244, v245
	v_pk_mul_f32 v[246:247], v[146:147], v[226:227]
	v_pk_fma_f32 v[246:247], v[138:139], v[210:211], v[246:247]
	v_pk_fma_f32 v[246:247], v[154:155], v[234:235], v[246:247]
	v_pk_mul_f32 v[246:247], v[246:247], v[242:243]
	v_cvt_pk_bf16_f32 v215, v246, v247
	s_add_u32 s18, s16, 0xa800
	s_addc_u32 s19, s17, 0
	global_store_dwordx4 v2, v[212:215], s[18:19]
	v_lshlrev_b32_e32 v204, 16, v96
	v_and_b32_e32 v205, 0xffff0000, v96
	v_lshlrev_b32_e32 v206, 16, v97
	v_and_b32_e32 v207, 0xffff0000, v97
	v_lshlrev_b32_e32 v208, 16, v98
	v_and_b32_e32 v209, 0xffff0000, v98
	v_lshlrev_b32_e32 v210, 16, v99
	v_and_b32_e32 v211, 0xffff0000, v99
	v_lshlrev_b32_e32 v236, 16, v128
	v_and_b32_e32 v237, 0xffff0000, v128
	v_lshlrev_b32_e32 v238, 16, v129
	v_and_b32_e32 v239, 0xffff0000, v129
	v_lshlrev_b32_e32 v240, 16, v130
	v_and_b32_e32 v241, 0xffff0000, v130
	v_lshlrev_b32_e32 v242, 16, v131
	v_and_b32_e32 v243, 0xffff0000, v131
	v_pk_mul_f32 v[244:245], v[140:141], v[228:229]
	v_pk_fma_f32 v[244:245], v[132:133], v[220:221], v[244:245]
	v_pk_fma_f32 v[244:245], v[148:149], v[204:205], v[244:245]
	v_pk_mul_f32 v[244:245], v[244:245], v[236:237]
	v_cvt_pk_bf16_f32 v216, v244, v245
	v_pk_mul_f32 v[246:247], v[142:143], v[230:231]
	v_pk_fma_f32 v[246:247], v[134:135], v[222:223], v[246:247]
	v_pk_fma_f32 v[246:247], v[150:151], v[206:207], v[246:247]
	v_pk_mul_f32 v[246:247], v[246:247], v[238:239]
	v_cvt_pk_bf16_f32 v217, v246, v247
	v_pk_mul_f32 v[244:245], v[144:145], v[232:233]
	v_pk_fma_f32 v[244:245], v[136:137], v[224:225], v[244:245]
	v_pk_fma_f32 v[244:245], v[152:153], v[208:209], v[244:245]
	v_pk_mul_f32 v[244:245], v[244:245], v[240:241]
	v_cvt_pk_bf16_f32 v218, v244, v245
	v_pk_mul_f32 v[246:247], v[146:147], v[234:235]
	v_pk_fma_f32 v[246:247], v[138:139], v[226:227], v[246:247]
	v_pk_fma_f32 v[246:247], v[154:155], v[210:211], v[246:247]
	v_pk_mul_f32 v[246:247], v[246:247], v[242:243]
	v_cvt_pk_bf16_f32 v219, v246, v247
	s_add_u32 s18, s16, 0xb400
	s_addc_u32 s19, s17, 0
	global_store_dwordx4 v2, v[216:219], s[18:19]
	s_add_u32 s18, s12, 0x4400
	s_addc_u32 s19, s13, 0
	s_add_u32 s30, s14, 0x4400
	s_addc_u32 s31, s15, 0
	global_load_dwordx4 v[68:71], v2, s[18:19]
	global_load_dwordx4 v[100:103], v2, s[30:31]
	s_add_u32 s18, s12, 0x4c00
	s_addc_u32 s19, s13, 0
	s_add_u32 s30, s14, 0x4c00
	s_addc_u32 s31, s15, 0
	global_load_dwordx4 v[72:75], v2, s[18:19]
	global_load_dwordx4 v[104:107], v2, s[30:31]
	s_add_u32 s18, s12, 0x5400
	s_addc_u32 s19, s13, 0
	s_add_u32 s30, s14, 0x5400
	s_addc_u32 s31, s15, 0
	global_load_dwordx4 v[76:79], v2, s[18:19]
	global_load_dwordx4 v[108:111], v2, s[30:31]
	s_add_u32 s18, s12, 0x5c00
	s_addc_u32 s19, s13, 0
	s_add_u32 s30, s14, 0x5c00
	s_addc_u32 s31, s15, 0
	global_load_dwordx4 v[80:83], v2, s[18:19]
	global_load_dwordx4 v[112:115], v2, s[30:31]
	s_add_u32 s18, s12, 0x6400
	s_addc_u32 s19, s13, 0
	s_add_u32 s30, s14, 0x6400
	s_addc_u32 s31, s15, 0
	global_load_dwordx4 v[84:87], v2, s[18:19]
	global_load_dwordx4 v[116:119], v2, s[30:31]
	s_add_u32 s18, s12, 0x6c00
	s_addc_u32 s19, s13, 0
	s_add_u32 s30, s14, 0x6c00
	s_addc_u32 s31, s15, 0
	global_load_dwordx4 v[88:91], v2, s[18:19]
	global_load_dwordx4 v[120:123], v2, s[30:31]
	s_add_u32 s18, s12, 0x7400
	s_addc_u32 s19, s13, 0
	s_add_u32 s30, s14, 0x7400
	s_addc_u32 s31, s15, 0
	global_load_dwordx4 v[92:95], v2, s[18:19]
	global_load_dwordx4 v[124:127], v2, s[30:31]
	s_add_u32 s18, s12, 0x7c00
	s_addc_u32 s19, s13, 0
	s_add_u32 s30, s14, 0x7c00
	s_addc_u32 s31, s15, 0
	global_load_dwordx4 v[96:99], v2, s[18:19]
	global_load_dwordx4 v[128:131], v2, s[30:31]
	s_waitcnt vmcnt(24)
	s_cmp_lg_u32 s21, 0
	s_cbranch_scc1 .Lcv_nz1
	v_mov_b32_e32 v188, 0
	v_mov_b32_e32 v189, 0
	v_mov_b32_e32 v190, 0
	v_mov_b32_e32 v191, 0
	v_mov_b32_e32 v196, 0
	v_mov_b32_e32 v197, 0
	v_mov_b32_e32 v198, 0
	v_mov_b32_e32 v199, 0
.Lcv_nz1:
	v_lshlrev_b32_e32 v220, 16, v196
	v_and_b32_e32 v221, 0xffff0000, v196
	v_lshlrev_b32_e32 v222, 16, v197
	v_and_b32_e32 v223, 0xffff0000, v197
	v_lshlrev_b32_e32 v224, 16, v198
	v_and_b32_e32 v225, 0xffff0000, v198
	v_lshlrev_b32_e32 v226, 16, v199
	v_and_b32_e32 v227, 0xffff0000, v199
	v_lshlrev_b32_e32 v228, 16, v188
	v_and_b32_e32 v229, 0xffff0000, v188
	v_lshlrev_b32_e32 v230, 16, v189
	v_and_b32_e32 v231, 0xffff0000, v189
	v_lshlrev_b32_e32 v232, 16, v190
	v_and_b32_e32 v233, 0xffff0000, v190
	v_lshlrev_b32_e32 v234, 16, v191
	v_and_b32_e32 v235, 0xffff0000, v191
	v_lshlrev_b32_e32 v204, 16, v4
	v_and_b32_e32 v205, 0xffff0000, v4
	v_lshlrev_b32_e32 v206, 16, v5
	v_and_b32_e32 v207, 0xffff0000, v5
	v_lshlrev_b32_e32 v208, 16, v6
	v_and_b32_e32 v209, 0xffff0000, v6
	v_lshlrev_b32_e32 v210, 16, v7
	v_and_b32_e32 v211, 0xffff0000, v7
	v_lshlrev_b32_e32 v236, 16, v36
	v_and_b32_e32 v237, 0xffff0000, v36
	v_lshlrev_b32_e32 v238, 16, v37
	v_and_b32_e32 v239, 0xffff0000, v37
	v_lshlrev_b32_e32 v240, 16, v38
	v_and_b32_e32 v241, 0xffff0000, v38
	v_lshlrev_b32_e32 v242, 16, v39
	v_and_b32_e32 v243, 0xffff0000, v39
	v_pk_mul_f32 v[244:245], v[164:165], v[228:229]
	v_pk_fma_f32 v[244:245], v[156:157], v[220:221], v[244:245]
	v_pk_fma_f32 v[244:245], v[172:173], v[204:205], v[244:245]
	v_pk_mul_f32 v[244:245], v[244:245], v[236:237]
	v_cvt_pk_bf16_f32 v212, v244, v245
	v_pk_mul_f32 v[246:247], v[166:167], v[230:231]
	v_pk_fma_f32 v[246:247], v[158:159], v[222:223], v[246:247]
	v_pk_fma_f32 v[246:247], v[174:175], v[206:207], v[246:247]
	v_pk_mul_f32 v[246:247], v[246:247], v[238:239]
	v_cvt_pk_bf16_f32 v213, v246, v247
	v_pk_mul_f32 v[244:245], v[168:169], v[232:233]
	v_pk_fma_f32 v[244:245], v[160:161], v[224:225], v[244:245]
	v_pk_fma_f32 v[244:245], v[176:177], v[208:209], v[244:245]
	v_pk_mul_f32 v[244:245], v[244:245], v[240:241]
	v_cvt_pk_bf16_f32 v214, v244, v245
	v_pk_mul_f32 v[246:247], v[170:171], v[234:235]
	v_pk_fma_f32 v[246:247], v[162:163], v[226:227], v[246:247]
	v_pk_fma_f32 v[246:247], v[178:179], v[210:211], v[246:247]
	v_pk_mul_f32 v[246:247], v[246:247], v[242:243]
	v_cvt_pk_bf16_f32 v215, v246, v247
	s_add_u32 s18, s16, 0x400
	s_addc_u32 s19, s17, 0
	global_store_dwordx4 v2, v[212:215], s[18:19]
	v_lshlrev_b32_e32 v220, 16, v8
	v_and_b32_e32 v221, 0xffff0000, v8
	v_lshlrev_b32_e32 v222, 16, v9
	v_and_b32_e32 v223, 0xffff0000, v9
	v_lshlrev_b32_e32 v224, 16, v10
	v_and_b32_e32 v225, 0xffff0000, v10
	v_lshlrev_b32_e32 v226, 16, v11
	v_and_b32_e32 v227, 0xffff0000, v11
	v_lshlrev_b32_e32 v236, 16, v40
	v_and_b32_e32 v237, 0xffff0000, v40
	v_lshlrev_b32_e32 v238, 16, v41
	v_and_b32_e32 v239, 0xffff0000, v41
	v_lshlrev_b32_e32 v240, 16, v42
	v_and_b32_e32 v241, 0xffff0000, v42
	v_lshlrev_b32_e32 v242, 16, v43
	v_and_b32_e32 v243, 0xffff0000, v43
	v_pk_mul_f32 v[244:245], v[164:165], v[204:205]
	v_pk_fma_f32 v[244:245], v[156:157], v[228:229], v[244:245]
	v_pk_fma_f32 v[244:245], v[172:173], v[220:221], v[244:245]
	v_pk_mul_f32 v[244:245], v[244:245], v[236:237]
	v_cvt_pk_bf16_f32 v216, v244, v245
	v_pk_mul_f32 v[246:247], v[166:167], v[206:207]
	v_pk_fma_f32 v[246:247], v[158:159], v[230:231], v[246:247]
	v_pk_fma_f32 v[246:247], v[174:175], v[222:223], v[246:247]
	v_pk_mul_f32 v[246:247], v[246:247], v[238:239]
	v_cvt_pk_bf16_f32 v217, v246, v247
	v_pk_mul_f32 v[244:245], v[168:169], v[208:209]
	v_pk_fma_f32 v[244:245], v[160:161], v[232:233], v[244:245]
	v_pk_fma_f32 v[244:245], v[176:177], v[224:225], v[244:245]
	v_pk_mul_f32 v[244:245], v[244:245], v[240:241]
	v_cvt_pk_bf16_f32 v218, v244, v245
	v_pk_mul_f32 v[246:247], v[170:171], v[210:211]
	v_pk_fma_f32 v[246:247], v[162:163], v[234:235], v[246:247]
	v_pk_fma_f32 v[246:247], v[178:179], v[226:227], v[246:247]
	v_pk_mul_f32 v[246:247], v[246:247], v[242:243]
	v_cvt_pk_bf16_f32 v219, v246, v247
	s_add_u32 s18, s16, 0x1000
	s_addc_u32 s19, s17, 0
	global_store_dwordx4 v2, v[216:219], s[18:19]
	v_lshlrev_b32_e32 v228, 16, v12
	v_and_b32_e32 v229, 0xffff0000, v12
	v_lshlrev_b32_e32 v230, 16, v13
	v_and_b32_e32 v231, 0xffff0000, v13
	v_lshlrev_b32_e32 v232, 16, v14
	v_and_b32_e32 v233, 0xffff0000, v14
	v_lshlrev_b32_e32 v234, 16, v15
	v_and_b32_e32 v235, 0xffff0000, v15
	v_lshlrev_b32_e32 v236, 16, v44
	v_and_b32_e32 v237, 0xffff0000, v44
	v_lshlrev_b32_e32 v238, 16, v45
	v_and_b32_e32 v239, 0xffff0000, v45
	v_lshlrev_b32_e32 v240, 16, v46
	v_and_b32_e32 v241, 0xffff0000, v46
	v_lshlrev_b32_e32 v242, 16, v47
	v_and_b32_e32 v243, 0xffff0000, v47
	v_pk_mul_f32 v[244:245], v[164:165], v[220:221]
	v_pk_fma_f32 v[244:245], v[156:157], v[204:205], v[244:245]
	v_pk_fma_f32 v[244:245], v[172:173], v[228:229], v[244:245]
	v_pk_mul_f32 v[244:245], v[244:245], v[236:237]
	v_cvt_pk_bf16_f32 v212, v244, v245
	v_pk_mul_f32 v[246:247], v[166:167], v[222:223]
	v_pk_fma_f32 v[246:247], v[158:159], v[206:207], v[246:247]
	v_pk_fma_f32 v[246:247], v[174:175], v[230:231], v[246:247]
	v_pk_mul_f32 v[246:247], v[246:247], v[238:239]
	v_cvt_pk_bf16_f32 v213, v246, v247
	v_pk_mul_f32 v[244:245], v[168:169], v[224:225]
	v_pk_fma_f32 v[244:245], v[160:161], v[208:209], v[244:245]
	v_pk_fma_f32 v[244:245], v[176:177], v[232:233], v[244:245]
	v_pk_mul_f32 v[244:245], v[244:245], v[240:241]
	v_cvt_pk_bf16_f32 v214, v244, v245
	v_pk_mul_f32 v[246:247], v[170:171], v[226:227]
	v_pk_fma_f32 v[246:247], v[162:163], v[210:211], v[246:247]
	v_pk_fma_f32 v[246:247], v[178:179], v[234:235], v[246:247]
	v_pk_mul_f32 v[246:247], v[246:247], v[242:243]
	v_cvt_pk_bf16_f32 v215, v246, v247
	s_add_u32 s18, s16, 0x1c00
	s_addc_u32 s19, s17, 0
	global_store_dwordx4 v2, v[212:215], s[18:19]
	v_lshlrev_b32_e32 v204, 16, v16
	v_and_b32_e32 v205, 0xffff0000, v16
	v_lshlrev_b32_e32 v206, 16, v17
	v_and_b32_e32 v207, 0xffff0000, v17
	v_lshlrev_b32_e32 v208, 16, v18
	v_and_b32_e32 v209, 0xffff0000, v18
	v_lshlrev_b32_e32 v210, 16, v19
	v_and_b32_e32 v211, 0xffff0000, v19
	v_lshlrev_b32_e32 v236, 16, v48
	v_and_b32_e32 v237, 0xffff0000, v48
	v_lshlrev_b32_e32 v238, 16, v49
	v_and_b32_e32 v239, 0xffff0000, v49
	v_lshlrev_b32_e32 v240, 16, v50
	v_and_b32_e32 v241, 0xffff0000, v50
	v_lshlrev_b32_e32 v242, 16, v51
	v_and_b32_e32 v243, 0xffff0000, v51
	v_pk_mul_f32 v[244:245], v[164:165], v[228:229]
	v_pk_fma_f32 v[244:245], v[156:157], v[220:221], v[244:245]
	v_pk_fma_f32 v[244:245], v[172:173], v[204:205], v[244:245]
	v_pk_mul_f32 v[244:245], v[244:245], v[236:237]
	v_cvt_pk_bf16_f32 v216, v244, v245
	v_pk_mul_f32 v[246:247], v[166:167], v[230:231]
	v_pk_fma_f32 v[246:247], v[158:159], v[222:223], v[246:247]
	v_pk_fma_f32 v[246:247], v[174:175], v[206:207], v[246:247]
	v_pk_mul_f32 v[246:247], v[246:247], v[238:239]
	v_cvt_pk_bf16_f32 v217, v246, v247
	v_pk_mul_f32 v[244:245], v[168:169], v[232:233]
	v_pk_fma_f32 v[244:245], v[160:161], v[224:225], v[244:245]
	v_pk_fma_f32 v[244:245], v[176:177], v[208:209], v[244:245]
	v_pk_mul_f32 v[244:245], v[244:245], v[240:241]
	v_cvt_pk_bf16_f32 v218, v244, v245
	v_pk_mul_f32 v[246:247], v[170:171], v[234:235]
	v_pk_fma_f32 v[246:247], v[162:163], v[226:227], v[246:247]
	v_pk_fma_f32 v[246:247], v[178:179], v[210:211], v[246:247]
	v_pk_mul_f32 v[246:247], v[246:247], v[242:243]
	v_cvt_pk_bf16_f32 v219, v246, v247
	s_add_u32 s18, s16, 0x2800
	s_addc_u32 s19, s17, 0
	global_store_dwordx4 v2, v[216:219], s[18:19]
	v_lshlrev_b32_e32 v220, 16, v20
	v_and_b32_e32 v221, 0xffff0000, v20
	v_lshlrev_b32_e32 v222, 16, v21
	v_and_b32_e32 v223, 0xffff0000, v21
	v_lshlrev_b32_e32 v224, 16, v22
	v_and_b32_e32 v225, 0xffff0000, v22
	v_lshlrev_b32_e32 v226, 16, v23
	v_and_b32_e32 v227, 0xffff0000, v23
	v_lshlrev_b32_e32 v236, 16, v52
	v_and_b32_e32 v237, 0xffff0000, v52
	v_lshlrev_b32_e32 v238, 16, v53
	v_and_b32_e32 v239, 0xffff0000, v53
	v_lshlrev_b32_e32 v240, 16, v54
	v_and_b32_e32 v241, 0xffff0000, v54
	v_lshlrev_b32_e32 v242, 16, v55
	v_and_b32_e32 v243, 0xffff0000, v55
	v_pk_mul_f32 v[244:245], v[164:165], v[204:205]
	v_pk_fma_f32 v[244:245], v[156:157], v[228:229], v[244:245]
	v_pk_fma_f32 v[244:245], v[172:173], v[220:221], v[244:245]
	v_pk_mul_f32 v[244:245], v[244:245], v[236:237]
	v_cvt_pk_bf16_f32 v212, v244, v245
	v_pk_mul_f32 v[246:247], v[166:167], v[206:207]
	v_pk_fma_f32 v[246:247], v[158:159], v[230:231], v[246:247]
	v_pk_fma_f32 v[246:247], v[174:175], v[222:223], v[246:247]
	v_pk_mul_f32 v[246:247], v[246:247], v[238:239]
	v_cvt_pk_bf16_f32 v213, v246, v247
	v_pk_mul_f32 v[244:245], v[168:169], v[208:209]
	v_pk_fma_f32 v[244:245], v[160:161], v[232:233], v[244:245]
	v_pk_fma_f32 v[244:245], v[176:177], v[224:225], v[244:245]
	v_pk_mul_f32 v[244:245], v[244:245], v[240:241]
	v_cvt_pk_bf16_f32 v214, v244, v245
	v_pk_mul_f32 v[246:247], v[170:171], v[210:211]
	v_pk_fma_f32 v[246:247], v[162:163], v[234:235], v[246:247]
	v_pk_fma_f32 v[246:247], v[178:179], v[226:227], v[246:247]
	v_pk_mul_f32 v[246:247], v[246:247], v[242:243]
	v_cvt_pk_bf16_f32 v215, v246, v247
	s_add_u32 s18, s16, 0x3400
	s_addc_u32 s19, s17, 0
	global_store_dwordx4 v2, v[212:215], s[18:19]
	v_lshlrev_b32_e32 v228, 16, v24
	v_and_b32_e32 v229, 0xffff0000, v24
	v_lshlrev_b32_e32 v230, 16, v25
	v_and_b32_e32 v231, 0xffff0000, v25
	v_lshlrev_b32_e32 v232, 16, v26
	v_and_b32_e32 v233, 0xffff0000, v26
	v_lshlrev_b32_e32 v234, 16, v27
	v_and_b32_e32 v235, 0xffff0000, v27
	v_lshlrev_b32_e32 v236, 16, v56
	v_and_b32_e32 v237, 0xffff0000, v56
	v_lshlrev_b32_e32 v238, 16, v57
	v_and_b32_e32 v239, 0xffff0000, v57
	v_lshlrev_b32_e32 v240, 16, v58
	v_and_b32_e32 v241, 0xffff0000, v58
	v_lshlrev_b32_e32 v242, 16, v59
	v_and_b32_e32 v243, 0xffff0000, v59
	v_pk_mul_f32 v[244:245], v[164:165], v[220:221]
	v_pk_fma_f32 v[244:245], v[156:157], v[204:205], v[244:245]
	v_pk_fma_f32 v[244:245], v[172:173], v[228:229], v[244:245]
	v_pk_mul_f32 v[244:245], v[244:245], v[236:237]
	v_cvt_pk_bf16_f32 v216, v244, v245
	v_pk_mul_f32 v[246:247], v[166:167], v[222:223]
	v_pk_fma_f32 v[246:247], v[158:159], v[206:207], v[246:247]
	v_pk_fma_f32 v[246:247], v[174:175], v[230:231], v[246:247]
	v_pk_mul_f32 v[246:247], v[246:247], v[238:239]
	v_cvt_pk_bf16_f32 v217, v246, v247
	v_pk_mul_f32 v[244:245], v[168:169], v[224:225]
	v_pk_fma_f32 v[244:245], v[160:161], v[208:209], v[244:245]
	v_pk_fma_f32 v[244:245], v[176:177], v[232:233], v[244:245]
	v_pk_mul_f32 v[244:245], v[244:245], v[240:241]
	v_cvt_pk_bf16_f32 v218, v244, v245
	v_pk_mul_f32 v[246:247], v[170:171], v[226:227]
	v_pk_fma_f32 v[246:247], v[162:163], v[210:211], v[246:247]
	v_pk_fma_f32 v[246:247], v[178:179], v[234:235], v[246:247]
	v_pk_mul_f32 v[246:247], v[246:247], v[242:243]
	v_cvt_pk_bf16_f32 v219, v246, v247
	s_add_u32 s18, s16, 0x4000
	s_addc_u32 s19, s17, 0
	global_store_dwordx4 v2, v[216:219], s[18:19]
	v_lshlrev_b32_e32 v204, 16, v28
	v_and_b32_e32 v205, 0xffff0000, v28
	v_lshlrev_b32_e32 v206, 16, v29
	v_and_b32_e32 v207, 0xffff0000, v29
	v_lshlrev_b32_e32 v208, 16, v30
	v_and_b32_e32 v209, 0xffff0000, v30
	v_lshlrev_b32_e32 v210, 16, v31
	v_and_b32_e32 v211, 0xffff0000, v31
	v_lshlrev_b32_e32 v236, 16, v60
	v_and_b32_e32 v237, 0xffff0000, v60
	v_lshlrev_b32_e32 v238, 16, v61
	v_and_b32_e32 v239, 0xffff0000, v61
	v_lshlrev_b32_e32 v240, 16, v62
	v_and_b32_e32 v241, 0xffff0000, v62
	v_lshlrev_b32_e32 v242, 16, v63
	v_and_b32_e32 v243, 0xffff0000, v63
	v_pk_mul_f32 v[244:245], v[164:165], v[228:229]
	v_pk_fma_f32 v[244:245], v[156:157], v[220:221], v[244:245]
	v_pk_fma_f32 v[244:245], v[172:173], v[204:205], v[244:245]
	v_pk_mul_f32 v[244:245], v[244:245], v[236:237]
	v_cvt_pk_bf16_f32 v212, v244, v245
	v_pk_mul_f32 v[246:247], v[166:167], v[230:231]
	v_pk_fma_f32 v[246:247], v[158:159], v[222:223], v[246:247]
	v_pk_fma_f32 v[246:247], v[174:175], v[206:207], v[246:247]
	v_pk_mul_f32 v[246:247], v[246:247], v[238:239]
	v_cvt_pk_bf16_f32 v213, v246, v247
	v_pk_mul_f32 v[244:245], v[168:169], v[232:233]
	v_pk_fma_f32 v[244:245], v[160:161], v[224:225], v[244:245]
	v_pk_fma_f32 v[244:245], v[176:177], v[208:209], v[244:245]
	v_pk_mul_f32 v[244:245], v[244:245], v[240:241]
	v_cvt_pk_bf16_f32 v214, v244, v245
	v_pk_mul_f32 v[246:247], v[170:171], v[234:235]
	v_pk_fma_f32 v[246:247], v[162:163], v[226:227], v[246:247]
	v_pk_fma_f32 v[246:247], v[178:179], v[210:211], v[246:247]
	v_pk_mul_f32 v[246:247], v[246:247], v[242:243]
	v_cvt_pk_bf16_f32 v215, v246, v247
	s_add_u32 s18, s16, 0x4c00
	s_addc_u32 s19, s17, 0
	global_store_dwordx4 v2, v[212:215], s[18:19]
	v_lshlrev_b32_e32 v220, 16, v32
	v_and_b32_e32 v221, 0xffff0000, v32
	v_lshlrev_b32_e32 v222, 16, v33
	v_and_b32_e32 v223, 0xffff0000, v33
	v_lshlrev_b32_e32 v224, 16, v34
	v_and_b32_e32 v225, 0xffff0000, v34
	v_lshlrev_b32_e32 v226, 16, v35
	v_and_b32_e32 v227, 0xffff0000, v35
	v_lshlrev_b32_e32 v236, 16, v64
	v_and_b32_e32 v237, 0xffff0000, v64
	v_lshlrev_b32_e32 v238, 16, v65
	v_and_b32_e32 v239, 0xffff0000, v65
	v_lshlrev_b32_e32 v240, 16, v66
	v_and_b32_e32 v241, 0xffff0000, v66
	v_lshlrev_b32_e32 v242, 16, v67
	v_and_b32_e32 v243, 0xffff0000, v67
	v_pk_mul_f32 v[244:245], v[164:165], v[204:205]
	v_pk_fma_f32 v[244:245], v[156:157], v[228:229], v[244:245]
	v_pk_fma_f32 v[244:245], v[172:173], v[220:221], v[244:245]
	v_pk_mul_f32 v[244:245], v[244:245], v[236:237]
	v_cvt_pk_bf16_f32 v216, v244, v245
	v_pk_mul_f32 v[246:247], v[166:167], v[206:207]
	v_pk_fma_f32 v[246:247], v[158:159], v[230:231], v[246:247]
	v_pk_fma_f32 v[246:247], v[174:175], v[222:223], v[246:247]
	v_pk_mul_f32 v[246:247], v[246:247], v[238:239]
	v_cvt_pk_bf16_f32 v217, v246, v247
	v_pk_mul_f32 v[244:245], v[168:169], v[208:209]
	v_pk_fma_f32 v[244:245], v[160:161], v[232:233], v[244:245]
	v_pk_fma_f32 v[244:245], v[176:177], v[224:225], v[244:245]
	v_pk_mul_f32 v[244:245], v[244:245], v[240:241]
	v_cvt_pk_bf16_f32 v218, v244, v245
	v_pk_mul_f32 v[246:247], v[170:171], v[210:211]
	v_pk_fma_f32 v[246:247], v[162:163], v[234:235], v[246:247]
	v_pk_fma_f32 v[246:247], v[178:179], v[226:227], v[246:247]
	v_pk_mul_f32 v[246:247], v[246:247], v[242:243]
	v_cvt_pk_bf16_f32 v219, v246, v247
	s_add_u32 s18, s16, 0x5800
	s_addc_u32 s19, s17, 0
	global_store_dwordx4 v2, v[216:219], s[18:19]
	s_waitcnt vmcnt(8)
	v_lshlrev_b32_e32 v228, 16, v68
	v_and_b32_e32 v229, 0xffff0000, v68
	v_lshlrev_b32_e32 v230, 16, v69
	v_and_b32_e32 v231, 0xffff0000, v69
	v_lshlrev_b32_e32 v232, 16, v70
	v_and_b32_e32 v233, 0xffff0000, v70
	v_lshlrev_b32_e32 v234, 16, v71
	v_and_b32_e32 v235, 0xffff0000, v71
	v_lshlrev_b32_e32 v236, 16, v100
	v_and_b32_e32 v237, 0xffff0000, v100
	v_lshlrev_b32_e32 v238, 16, v101
	v_and_b32_e32 v239, 0xffff0000, v101
	v_lshlrev_b32_e32 v240, 16, v102
	v_and_b32_e32 v241, 0xffff0000, v102
	v_lshlrev_b32_e32 v242, 16, v103
	v_and_b32_e32 v243, 0xffff0000, v103
	v_pk_mul_f32 v[244:245], v[164:165], v[220:221]
	v_pk_fma_f32 v[244:245], v[156:157], v[204:205], v[244:245]
	v_pk_fma_f32 v[244:245], v[172:173], v[228:229], v[244:245]
	v_pk_mul_f32 v[244:245], v[244:245], v[236:237]
	v_cvt_pk_bf16_f32 v212, v244, v245
	v_pk_mul_f32 v[246:247], v[166:167], v[222:223]
	v_pk_fma_f32 v[246:247], v[158:159], v[206:207], v[246:247]
	v_pk_fma_f32 v[246:247], v[174:175], v[230:231], v[246:247]
	v_pk_mul_f32 v[246:247], v[246:247], v[238:239]
	v_cvt_pk_bf16_f32 v213, v246, v247
	v_pk_mul_f32 v[244:245], v[168:169], v[224:225]
	v_pk_fma_f32 v[244:245], v[160:161], v[208:209], v[244:245]
	v_pk_fma_f32 v[244:245], v[176:177], v[232:233], v[244:245]
	v_pk_mul_f32 v[244:245], v[244:245], v[240:241]
	v_cvt_pk_bf16_f32 v214, v244, v245
	v_pk_mul_f32 v[246:247], v[170:171], v[226:227]
	v_pk_fma_f32 v[246:247], v[162:163], v[210:211], v[246:247]
	v_pk_fma_f32 v[246:247], v[178:179], v[234:235], v[246:247]
	v_pk_mul_f32 v[246:247], v[246:247], v[242:243]
	v_cvt_pk_bf16_f32 v215, v246, v247
	s_add_u32 s18, s16, 0x6400
	s_addc_u32 s19, s17, 0
	global_store_dwordx4 v2, v[212:215], s[18:19]
	v_lshlrev_b32_e32 v204, 16, v72
	v_and_b32_e32 v205, 0xffff0000, v72
	v_lshlrev_b32_e32 v206, 16, v73
	v_and_b32_e32 v207, 0xffff0000, v73
	v_lshlrev_b32_e32 v208, 16, v74
	v_and_b32_e32 v209, 0xffff0000, v74
	v_lshlrev_b32_e32 v210, 16, v75
	v_and_b32_e32 v211, 0xffff0000, v75
	v_lshlrev_b32_e32 v236, 16, v104
	v_and_b32_e32 v237, 0xffff0000, v104
	v_lshlrev_b32_e32 v238, 16, v105
	v_and_b32_e32 v239, 0xffff0000, v105
	v_lshlrev_b32_e32 v240, 16, v106
	v_and_b32_e32 v241, 0xffff0000, v106
	v_lshlrev_b32_e32 v242, 16, v107
	v_and_b32_e32 v243, 0xffff0000, v107
	v_pk_mul_f32 v[244:245], v[164:165], v[228:229]
	v_pk_fma_f32 v[244:245], v[156:157], v[220:221], v[244:245]
	v_pk_fma_f32 v[244:245], v[172:173], v[204:205], v[244:245]
	v_pk_mul_f32 v[244:245], v[244:245], v[236:237]
	v_cvt_pk_bf16_f32 v216, v244, v245
	v_pk_mul_f32 v[246:247], v[166:167], v[230:231]
	v_pk_fma_f32 v[246:247], v[158:159], v[222:223], v[246:247]
	v_pk_fma_f32 v[246:247], v[174:175], v[206:207], v[246:247]
	v_pk_mul_f32 v[246:247], v[246:247], v[238:239]
	v_cvt_pk_bf16_f32 v217, v246, v247
	v_pk_mul_f32 v[244:245], v[168:169], v[232:233]
	v_pk_fma_f32 v[244:245], v[160:161], v[224:225], v[244:245]
	v_pk_fma_f32 v[244:245], v[176:177], v[208:209], v[244:245]
	v_pk_mul_f32 v[244:245], v[244:245], v[240:241]
	v_cvt_pk_bf16_f32 v218, v244, v245
	v_pk_mul_f32 v[246:247], v[170:171], v[234:235]
	v_pk_fma_f32 v[246:247], v[162:163], v[226:227], v[246:247]
	v_pk_fma_f32 v[246:247], v[178:179], v[210:211], v[246:247]
	v_pk_mul_f32 v[246:247], v[246:247], v[242:243]
	v_cvt_pk_bf16_f32 v219, v246, v247
	s_add_u32 s18, s16, 0x7000
	s_addc_u32 s19, s17, 0
	global_store_dwordx4 v2, v[216:219], s[18:19]
	v_lshlrev_b32_e32 v220, 16, v76
	v_and_b32_e32 v221, 0xffff0000, v76
	v_lshlrev_b32_e32 v222, 16, v77
	v_and_b32_e32 v223, 0xffff0000, v77
	v_lshlrev_b32_e32 v224, 16, v78
	v_and_b32_e32 v225, 0xffff0000, v78
	v_lshlrev_b32_e32 v226, 16, v79
	v_and_b32_e32 v227, 0xffff0000, v79
	v_lshlrev_b32_e32 v236, 16, v108
	v_and_b32_e32 v237, 0xffff0000, v108
	v_lshlrev_b32_e32 v238, 16, v109
	v_and_b32_e32 v239, 0xffff0000, v109
	v_lshlrev_b32_e32 v240, 16, v110
	v_and_b32_e32 v241, 0xffff0000, v110
	v_lshlrev_b32_e32 v242, 16, v111
	v_and_b32_e32 v243, 0xffff0000, v111
	v_pk_mul_f32 v[244:245], v[164:165], v[204:205]
	v_pk_fma_f32 v[244:245], v[156:157], v[228:229], v[244:245]
	v_pk_fma_f32 v[244:245], v[172:173], v[220:221], v[244:245]
	v_pk_mul_f32 v[244:245], v[244:245], v[236:237]
	v_cvt_pk_bf16_f32 v212, v244, v245
	v_pk_mul_f32 v[246:247], v[166:167], v[206:207]
	v_pk_fma_f32 v[246:247], v[158:159], v[230:231], v[246:247]
	v_pk_fma_f32 v[246:247], v[174:175], v[222:223], v[246:247]
	v_pk_mul_f32 v[246:247], v[246:247], v[238:239]
	v_cvt_pk_bf16_f32 v213, v246, v247
	v_pk_mul_f32 v[244:245], v[168:169], v[208:209]
	v_pk_fma_f32 v[244:245], v[160:161], v[232:233], v[244:245]
	v_pk_fma_f32 v[244:245], v[176:177], v[224:225], v[244:245]
	v_pk_mul_f32 v[244:245], v[244:245], v[240:241]
	v_cvt_pk_bf16_f32 v214, v244, v245
	v_pk_mul_f32 v[246:247], v[170:171], v[210:211]
	v_pk_fma_f32 v[246:247], v[162:163], v[234:235], v[246:247]
	v_pk_fma_f32 v[246:247], v[178:179], v[226:227], v[246:247]
	v_pk_mul_f32 v[246:247], v[246:247], v[242:243]
	v_cvt_pk_bf16_f32 v215, v246, v247
	s_add_u32 s18, s16, 0x7c00
	s_addc_u32 s19, s17, 0
	global_store_dwordx4 v2, v[212:215], s[18:19]
	v_lshlrev_b32_e32 v228, 16, v80
	v_and_b32_e32 v229, 0xffff0000, v80
	v_lshlrev_b32_e32 v230, 16, v81
	v_and_b32_e32 v231, 0xffff0000, v81
	v_lshlrev_b32_e32 v232, 16, v82
	v_and_b32_e32 v233, 0xffff0000, v82
	v_lshlrev_b32_e32 v234, 16, v83
	v_and_b32_e32 v235, 0xffff0000, v83
	v_lshlrev_b32_e32 v236, 16, v112
	v_and_b32_e32 v237, 0xffff0000, v112
	v_lshlrev_b32_e32 v238, 16, v113
	v_and_b32_e32 v239, 0xffff0000, v113
	v_lshlrev_b32_e32 v240, 16, v114
	v_and_b32_e32 v241, 0xffff0000, v114
	v_lshlrev_b32_e32 v242, 16, v115
	v_and_b32_e32 v243, 0xffff0000, v115
	v_pk_mul_f32 v[244:245], v[164:165], v[220:221]
	v_pk_fma_f32 v[244:245], v[156:157], v[204:205], v[244:245]
	v_pk_fma_f32 v[244:245], v[172:173], v[228:229], v[244:245]
	v_pk_mul_f32 v[244:245], v[244:245], v[236:237]
	v_cvt_pk_bf16_f32 v216, v244, v245
	v_pk_mul_f32 v[246:247], v[166:167], v[222:223]
	v_pk_fma_f32 v[246:247], v[158:159], v[206:207], v[246:247]
	v_pk_fma_f32 v[246:247], v[174:175], v[230:231], v[246:247]
	v_pk_mul_f32 v[246:247], v[246:247], v[238:239]
	v_cvt_pk_bf16_f32 v217, v246, v247
	v_pk_mul_f32 v[244:245], v[168:169], v[224:225]
	v_pk_fma_f32 v[244:245], v[160:161], v[208:209], v[244:245]
	v_pk_fma_f32 v[244:245], v[176:177], v[232:233], v[244:245]
	v_pk_mul_f32 v[244:245], v[244:245], v[240:241]
	v_cvt_pk_bf16_f32 v218, v244, v245
	v_pk_mul_f32 v[246:247], v[170:171], v[226:227]
	v_pk_fma_f32 v[246:247], v[162:163], v[210:211], v[246:247]
	v_pk_fma_f32 v[246:247], v[178:179], v[234:235], v[246:247]
	v_pk_mul_f32 v[246:247], v[246:247], v[242:243]
	v_cvt_pk_bf16_f32 v219, v246, v247
	s_add_u32 s18, s16, 0x8800
	s_addc_u32 s19, s17, 0
	global_store_dwordx4 v2, v[216:219], s[18:19]
	v_lshlrev_b32_e32 v204, 16, v84
	v_and_b32_e32 v205, 0xffff0000, v84
	v_lshlrev_b32_e32 v206, 16, v85
	v_and_b32_e32 v207, 0xffff0000, v85
	v_lshlrev_b32_e32 v208, 16, v86
	v_and_b32_e32 v209, 0xffff0000, v86
	v_lshlrev_b32_e32 v210, 16, v87
	v_and_b32_e32 v211, 0xffff0000, v87
	v_lshlrev_b32_e32 v236, 16, v116
	v_and_b32_e32 v237, 0xffff0000, v116
	v_lshlrev_b32_e32 v238, 16, v117
	v_and_b32_e32 v239, 0xffff0000, v117
	v_lshlrev_b32_e32 v240, 16, v118
	v_and_b32_e32 v241, 0xffff0000, v118
	v_lshlrev_b32_e32 v242, 16, v119
	v_and_b32_e32 v243, 0xffff0000, v119
	v_pk_mul_f32 v[244:245], v[164:165], v[228:229]
	v_pk_fma_f32 v[244:245], v[156:157], v[220:221], v[244:245]
	v_pk_fma_f32 v[244:245], v[172:173], v[204:205], v[244:245]
	v_pk_mul_f32 v[244:245], v[244:245], v[236:237]
	v_cvt_pk_bf16_f32 v212, v244, v245
	v_pk_mul_f32 v[246:247], v[166:167], v[230:231]
	v_pk_fma_f32 v[246:247], v[158:159], v[222:223], v[246:247]
	v_pk_fma_f32 v[246:247], v[174:175], v[206:207], v[246:247]
	v_pk_mul_f32 v[246:247], v[246:247], v[238:239]
	v_cvt_pk_bf16_f32 v213, v246, v247
	v_pk_mul_f32 v[244:245], v[168:169], v[232:233]
	v_pk_fma_f32 v[244:245], v[160:161], v[224:225], v[244:245]
	v_pk_fma_f32 v[244:245], v[176:177], v[208:209], v[244:245]
	v_pk_mul_f32 v[244:245], v[244:245], v[240:241]
	v_cvt_pk_bf16_f32 v214, v244, v245
	v_pk_mul_f32 v[246:247], v[170:171], v[234:235]
	v_pk_fma_f32 v[246:247], v[162:163], v[226:227], v[246:247]
	v_pk_fma_f32 v[246:247], v[178:179], v[210:211], v[246:247]
	v_pk_mul_f32 v[246:247], v[246:247], v[242:243]
	v_cvt_pk_bf16_f32 v215, v246, v247
	s_add_u32 s18, s16, 0x9400
	s_addc_u32 s19, s17, 0
	global_store_dwordx4 v2, v[212:215], s[18:19]
	v_lshlrev_b32_e32 v220, 16, v88
	v_and_b32_e32 v221, 0xffff0000, v88
	v_lshlrev_b32_e32 v222, 16, v89
	v_and_b32_e32 v223, 0xffff0000, v89
	v_lshlrev_b32_e32 v224, 16, v90
	v_and_b32_e32 v225, 0xffff0000, v90
	v_lshlrev_b32_e32 v226, 16, v91
	v_and_b32_e32 v227, 0xffff0000, v91
	v_lshlrev_b32_e32 v236, 16, v120
	v_and_b32_e32 v237, 0xffff0000, v120
	v_lshlrev_b32_e32 v238, 16, v121
	v_and_b32_e32 v239, 0xffff0000, v121
	v_lshlrev_b32_e32 v240, 16, v122
	v_and_b32_e32 v241, 0xffff0000, v122
	v_lshlrev_b32_e32 v242, 16, v123
	v_and_b32_e32 v243, 0xffff0000, v123
	v_pk_mul_f32 v[244:245], v[164:165], v[204:205]
	v_pk_fma_f32 v[244:245], v[156:157], v[228:229], v[244:245]
	v_pk_fma_f32 v[244:245], v[172:173], v[220:221], v[244:245]
	v_pk_mul_f32 v[244:245], v[244:245], v[236:237]
	v_cvt_pk_bf16_f32 v216, v244, v245
	v_pk_mul_f32 v[246:247], v[166:167], v[206:207]
	v_pk_fma_f32 v[246:247], v[158:159], v[230:231], v[246:247]
	v_pk_fma_f32 v[246:247], v[174:175], v[222:223], v[246:247]
	v_pk_mul_f32 v[246:247], v[246:247], v[238:239]
	v_cvt_pk_bf16_f32 v217, v246, v247
	v_pk_mul_f32 v[244:245], v[168:169], v[208:209]
	v_pk_fma_f32 v[244:245], v[160:161], v[232:233], v[244:245]
	v_pk_fma_f32 v[244:245], v[176:177], v[224:225], v[244:245]
	v_pk_mul_f32 v[244:245], v[244:245], v[240:241]
	v_cvt_pk_bf16_f32 v218, v244, v245
	v_pk_mul_f32 v[246:247], v[170:171], v[210:211]
	v_pk_fma_f32 v[246:247], v[162:163], v[234:235], v[246:247]
	v_pk_fma_f32 v[246:247], v[178:179], v[226:227], v[246:247]
	v_pk_mul_f32 v[246:247], v[246:247], v[242:243]
	v_cvt_pk_bf16_f32 v219, v246, v247
	s_add_u32 s18, s16, 0xa000
	s_addc_u32 s19, s17, 0
	global_store_dwordx4 v2, v[216:219], s[18:19]
	v_lshlrev_b32_e32 v228, 16, v92
	v_and_b32_e32 v229, 0xffff0000, v92
	v_lshlrev_b32_e32 v230, 16, v93
	v_and_b32_e32 v231, 0xffff0000, v93
	v_lshlrev_b32_e32 v232, 16, v94
	v_and_b32_e32 v233, 0xffff0000, v94
	v_lshlrev_b32_e32 v234, 16, v95
	v_and_b32_e32 v235, 0xffff0000, v95
	v_lshlrev_b32_e32 v236, 16, v124
	v_and_b32_e32 v237, 0xffff0000, v124
	v_lshlrev_b32_e32 v238, 16, v125
	v_and_b32_e32 v239, 0xffff0000, v125
	v_lshlrev_b32_e32 v240, 16, v126
	v_and_b32_e32 v241, 0xffff0000, v126
	v_lshlrev_b32_e32 v242, 16, v127
	v_and_b32_e32 v243, 0xffff0000, v127
	v_pk_mul_f32 v[244:245], v[164:165], v[220:221]
	v_pk_fma_f32 v[244:245], v[156:157], v[204:205], v[244:245]
	v_pk_fma_f32 v[244:245], v[172:173], v[228:229], v[244:245]
	v_pk_mul_f32 v[244:245], v[244:245], v[236:237]
	v_cvt_pk_bf16_f32 v212, v244, v245
	v_pk_mul_f32 v[246:247], v[166:167], v[222:223]
	v_pk_fma_f32 v[246:247], v[158:159], v[206:207], v[246:247]
	v_pk_fma_f32 v[246:247], v[174:175], v[230:231], v[246:247]
	v_pk_mul_f32 v[246:247], v[246:247], v[238:239]
	v_cvt_pk_bf16_f32 v213, v246, v247
	v_pk_mul_f32 v[244:245], v[168:169], v[224:225]
	v_pk_fma_f32 v[244:245], v[160:161], v[208:209], v[244:245]
	v_pk_fma_f32 v[244:245], v[176:177], v[232:233], v[244:245]
	v_pk_mul_f32 v[244:245], v[244:245], v[240:241]
	v_cvt_pk_bf16_f32 v214, v244, v245
	v_pk_mul_f32 v[246:247], v[170:171], v[226:227]
	v_pk_fma_f32 v[246:247], v[162:163], v[210:211], v[246:247]
	v_pk_fma_f32 v[246:247], v[178:179], v[234:235], v[246:247]
	v_pk_mul_f32 v[246:247], v[246:247], v[242:243]
	v_cvt_pk_bf16_f32 v215, v246, v247
	s_add_u32 s18, s16, 0xac00
	s_addc_u32 s19, s17, 0
	global_store_dwordx4 v2, v[212:215], s[18:19]
	v_lshlrev_b32_e32 v204, 16, v96
	v_and_b32_e32 v205, 0xffff0000, v96
	v_lshlrev_b32_e32 v206, 16, v97
	v_and_b32_e32 v207, 0xffff0000, v97
	v_lshlrev_b32_e32 v208, 16, v98
	v_and_b32_e32 v209, 0xffff0000, v98
	v_lshlrev_b32_e32 v210, 16, v99
	v_and_b32_e32 v211, 0xffff0000, v99
	v_lshlrev_b32_e32 v236, 16, v128
	v_and_b32_e32 v237, 0xffff0000, v128
	v_lshlrev_b32_e32 v238, 16, v129
	v_and_b32_e32 v239, 0xffff0000, v129
	v_lshlrev_b32_e32 v240, 16, v130
	v_and_b32_e32 v241, 0xffff0000, v130
	v_lshlrev_b32_e32 v242, 16, v131
	v_and_b32_e32 v243, 0xffff0000, v131
	v_pk_mul_f32 v[244:245], v[164:165], v[228:229]
	v_pk_fma_f32 v[244:245], v[156:157], v[220:221], v[244:245]
	v_pk_fma_f32 v[244:245], v[172:173], v[204:205], v[244:245]
	v_pk_mul_f32 v[244:245], v[244:245], v[236:237]
	v_cvt_pk_bf16_f32 v216, v244, v245
	v_pk_mul_f32 v[246:247], v[166:167], v[230:231]
	v_pk_fma_f32 v[246:247], v[158:159], v[222:223], v[246:247]
	v_pk_fma_f32 v[246:247], v[174:175], v[206:207], v[246:247]
	v_pk_mul_f32 v[246:247], v[246:247], v[238:239]
	v_cvt_pk_bf16_f32 v217, v246, v247
	v_pk_mul_f32 v[244:245], v[168:169], v[232:233]
	v_pk_fma_f32 v[244:245], v[160:161], v[224:225], v[244:245]
	v_pk_fma_f32 v[244:245], v[176:177], v[208:209], v[244:245]
	v_pk_mul_f32 v[244:245], v[244:245], v[240:241]
	v_cvt_pk_bf16_f32 v218, v244, v245
	v_pk_mul_f32 v[246:247], v[170:171], v[234:235]
	v_pk_fma_f32 v[246:247], v[162:163], v[226:227], v[246:247]
	v_pk_fma_f32 v[246:247], v[178:179], v[210:211], v[246:247]
	v_pk_mul_f32 v[246:247], v[246:247], v[242:243]
	v_cvt_pk_bf16_f32 v219, v246, v247
	s_add_u32 s18, s16, 0xb800
	s_addc_u32 s19, s17, 0
	global_store_dwordx4 v2, v[216:219], s[18:19]
	v_mov_b32_e32 v164, v200
	v_mbcnt_hi_u32_b32 v155, -1, v194
	v_and_b32_e32 v0, 64, v155
	v_mov_b32_e32 v154, 0x358637bd
	v_xor_b32_e32 v156, 32, v155
	v_add_u32_e32 v157, 64, v0
	v_mov_b32_e32 v158, 0xf149f2ca
	v_mov_b32_e32 v159, 0x7149f2ca
	v_mov_b32_e32 v160, 0x2080
	v_mov_b32_e32 v161, 0x461c4000
	v_mov_b32_e32 v162, 0xffffff80
	v_mov_b32_e32 v163, 0x63
	s_branch .Lp3_item_end
